# unrolled GEMM loops: each LDS-DMA tile load placed between two MFMAs (the MFMA covers the m0 hazard slot, no s_nop, loads spread over the step)
# speedup vs baseline: 1.0168x; 1.0040x over previous
.Lg1_loop:
	ds_read_b128 v[126:129], v217
	ds_read_b128 v[134:137], v221
	ds_read_b128 v[138:141], v221 offset:4096
	ds_read_b128 v[130:133], v217 offset:4096
	s_setprio 1
	s_add_i32 m0, s79, 0x1b900
	s_waitcnt lgkmcnt(6)
	v_mfma_f32_32x32x16_bf16 v[50:65], v[108:111], v[116:119], v[50:65]
	global_load_lds_dwordx4 v144, s[72:73]
	s_add_i32 m0, s79, 0x1d900
	s_waitcnt lgkmcnt(5)
	v_mfma_f32_32x32x16_bf16 v[18:33], v[108:111], v[120:123], v[18:33]
	global_load_lds_dwordx4 v145, s[72:73]
	s_waitcnt lgkmcnt(4)
	v_mfma_f32_32x32x16_bf16 v[34:49], v[112:115], v[116:119], v[34:49]
	v_mfma_f32_32x32x16_bf16 v[2:17], v[112:115], v[120:123], v[2:17]
	s_setprio 0
	ds_read_b128 v[108:111], v218
	ds_read_b128 v[116:119], v222
	ds_read_b128 v[120:123], v222 offset:4096
	ds_read_b128 v[112:115], v218 offset:4096
	s_setprio 1
	s_add_i32 m0, s79, 0x1f900
	s_waitcnt lgkmcnt(6)
	v_mfma_f32_32x32x16_bf16 v[50:65], v[126:129], v[134:137], v[50:65]
	global_load_lds_dwordx4 v144, s[74:75]
	s_add_i32 m0, s79, 0x21900
	s_waitcnt lgkmcnt(5)
	v_mfma_f32_32x32x16_bf16 v[18:33], v[126:129], v[138:141], v[18:33]
	global_load_lds_dwordx4 v145, s[74:75]
	s_waitcnt lgkmcnt(4)
	v_mfma_f32_32x32x16_bf16 v[34:49], v[130:133], v[134:137], v[34:49]
	v_mfma_f32_32x32x16_bf16 v[2:17], v[130:133], v[138:141], v[2:17]
	s_setprio 0
	ds_read_b128 v[126:129], v219
	ds_read_b128 v[134:137], v223
	ds_read_b128 v[138:141], v223 offset:4096
	ds_read_b128 v[130:133], v219 offset:4096
	s_setprio 1
	s_add_i32 m0, s79, 0x23900
	s_waitcnt lgkmcnt(6)
	v_mfma_f32_32x32x16_bf16 v[50:65], v[108:111], v[116:119], v[50:65]
	global_load_lds_dwordx4 v146, s[74:75]
	s_add_i32 m0, s79, 0x25900
	s_waitcnt lgkmcnt(5)
	v_mfma_f32_32x32x16_bf16 v[18:33], v[108:111], v[120:123], v[18:33]
	global_load_lds_dwordx4 v147, s[74:75]
	s_waitcnt lgkmcnt(4)
	v_mfma_f32_32x32x16_bf16 v[34:49], v[112:115], v[116:119], v[34:49]
	v_mfma_f32_32x32x16_bf16 v[2:17], v[112:115], v[120:123], v[2:17]
	s_setprio 0
	s_add_u32 s72, s72, 0x80
	s_addc_u32 s73, s73, 0
	s_add_u32 s74, s74, 0x80
	s_addc_u32 s75, s75, 0
	s_waitcnt lgkmcnt(0)
	s_waitcnt vmcnt(6)
	s_barrier
	ds_read_b128 v[108:111], v216 offset:49152
	ds_read_b128 v[116:119], v220 offset:49152
	ds_read_b128 v[120:123], v220 offset:53248
	ds_read_b128 v[112:115], v216 offset:53248
	s_setprio 1
	v_mfma_f32_32x32x16_bf16 v[50:65], v[126:129], v[134:137], v[50:65]
	v_mfma_f32_32x32x16_bf16 v[18:33], v[126:129], v[138:141], v[18:33]
	v_mfma_f32_32x32x16_bf16 v[34:49], v[130:133], v[134:137], v[34:49]
	v_mfma_f32_32x32x16_bf16 v[2:17], v[130:133], v[138:141], v[2:17]
	s_setprio 0
	ds_read_b128 v[126:129], v217 offset:49152
	ds_read_b128 v[134:137], v221 offset:49152
	ds_read_b128 v[138:141], v221 offset:53248
	ds_read_b128 v[130:133], v217 offset:53248
	s_setprio 1
	s_add_i32 m0, s79, 0x100
	s_waitcnt lgkmcnt(6)
	v_mfma_f32_32x32x16_bf16 v[50:65], v[108:111], v[116:119], v[50:65]
	global_load_lds_dwordx4 v144, s[72:73]
	s_add_i32 m0, s79, 0x2100
	s_waitcnt lgkmcnt(5)
	v_mfma_f32_32x32x16_bf16 v[18:33], v[108:111], v[120:123], v[18:33]
	global_load_lds_dwordx4 v145, s[72:73]
	s_waitcnt lgkmcnt(4)
	v_mfma_f32_32x32x16_bf16 v[34:49], v[112:115], v[116:119], v[34:49]
	v_mfma_f32_32x32x16_bf16 v[2:17], v[112:115], v[120:123], v[2:17]
	s_setprio 0
	ds_read_b128 v[108:111], v218 offset:49152
	ds_read_b128 v[116:119], v222 offset:49152
	ds_read_b128 v[120:123], v222 offset:53248
	ds_read_b128 v[112:115], v218 offset:53248
	s_setprio 1
	s_add_i32 m0, s79, 0x4100
	s_waitcnt lgkmcnt(6)
	v_mfma_f32_32x32x16_bf16 v[50:65], v[126:129], v[134:137], v[50:65]
	global_load_lds_dwordx4 v144, s[74:75]
	s_add_i32 m0, s79, 0x6100
	s_waitcnt lgkmcnt(5)
	v_mfma_f32_32x32x16_bf16 v[18:33], v[126:129], v[138:141], v[18:33]
	global_load_lds_dwordx4 v145, s[74:75]
	s_waitcnt lgkmcnt(4)
	v_mfma_f32_32x32x16_bf16 v[34:49], v[130:133], v[134:137], v[34:49]
	v_mfma_f32_32x32x16_bf16 v[2:17], v[130:133], v[138:141], v[2:17]
	s_setprio 0
	ds_read_b128 v[126:129], v219 offset:49152
	ds_read_b128 v[134:137], v223 offset:49152
	ds_read_b128 v[138:141], v223 offset:53248
	ds_read_b128 v[130:133], v219 offset:53248
	s_setprio 1
	s_add_i32 m0, s79, 0x8100
	s_waitcnt lgkmcnt(6)
	v_mfma_f32_32x32x16_bf16 v[50:65], v[108:111], v[116:119], v[50:65]
	global_load_lds_dwordx4 v146, s[74:75]
	s_add_i32 m0, s79, 0xa100
	s_waitcnt lgkmcnt(5)
	v_mfma_f32_32x32x16_bf16 v[18:33], v[108:111], v[120:123], v[18:33]
	global_load_lds_dwordx4 v147, s[74:75]
	s_waitcnt lgkmcnt(4)
	v_mfma_f32_32x32x16_bf16 v[34:49], v[112:115], v[116:119], v[34:49]
	v_mfma_f32_32x32x16_bf16 v[2:17], v[112:115], v[120:123], v[2:17]
	s_setprio 0
	s_add_u32 s72, s72, 0x80
	s_addc_u32 s73, s73, 0
	s_add_u32 s74, s74, 0x80
	s_addc_u32 s75, s75, 0
	s_waitcnt lgkmcnt(0)
	s_waitcnt vmcnt(6)
	s_barrier
	ds_read_b128 v[108:111], v224
	ds_read_b128 v[116:119], v228
	ds_read_b128 v[120:123], v228 offset:4096
	ds_read_b128 v[112:115], v224 offset:4096
	s_setprio 1
	v_mfma_f32_32x32x16_bf16 v[50:65], v[126:129], v[134:137], v[50:65]
	v_mfma_f32_32x32x16_bf16 v[18:33], v[126:129], v[138:141], v[18:33]
	v_mfma_f32_32x32x16_bf16 v[34:49], v[130:133], v[134:137], v[34:49]
	v_mfma_f32_32x32x16_bf16 v[2:17], v[130:133], v[138:141], v[2:17]
	s_setprio 0
	ds_read_b128 v[126:129], v225
	ds_read_b128 v[134:137], v229
	ds_read_b128 v[138:141], v229 offset:4096
	ds_read_b128 v[130:133], v225 offset:4096
	s_setprio 1
	s_add_i32 m0, s79, 0xc100
	s_waitcnt lgkmcnt(6)
	v_mfma_f32_32x32x16_bf16 v[50:65], v[108:111], v[116:119], v[50:65]
	global_load_lds_dwordx4 v144, s[72:73]
	s_add_i32 m0, s79, 0xe100
	s_waitcnt lgkmcnt(5)
	v_mfma_f32_32x32x16_bf16 v[18:33], v[108:111], v[120:123], v[18:33]
	global_load_lds_dwordx4 v145, s[72:73]
	s_waitcnt lgkmcnt(4)
	v_mfma_f32_32x32x16_bf16 v[34:49], v[112:115], v[116:119], v[34:49]
	v_mfma_f32_32x32x16_bf16 v[2:17], v[112:115], v[120:123], v[2:17]
	s_setprio 0
	ds_read_b128 v[108:111], v226
	ds_read_b128 v[116:119], v230
	ds_read_b128 v[120:123], v230 offset:4096
	ds_read_b128 v[112:115], v226 offset:4096
	s_setprio 1
	s_add_i32 m0, s79, 0x10100
	s_waitcnt lgkmcnt(6)
	v_mfma_f32_32x32x16_bf16 v[50:65], v[126:129], v[134:137], v[50:65]
	global_load_lds_dwordx4 v144, s[74:75]
	s_add_i32 m0, s79, 0x12100
	s_waitcnt lgkmcnt(5)
	v_mfma_f32_32x32x16_bf16 v[18:33], v[126:129], v[138:141], v[18:33]
	global_load_lds_dwordx4 v145, s[74:75]
	s_waitcnt lgkmcnt(4)
	v_mfma_f32_32x32x16_bf16 v[34:49], v[130:133], v[134:137], v[34:49]
	v_mfma_f32_32x32x16_bf16 v[2:17], v[130:133], v[138:141], v[2:17]
	s_setprio 0
	ds_read_b128 v[126:129], v227
	ds_read_b128 v[134:137], v231
	ds_read_b128 v[138:141], v231 offset:4096
	ds_read_b128 v[130:133], v227 offset:4096
	s_setprio 1
	s_add_i32 m0, s79, 0x14100
	s_waitcnt lgkmcnt(6)
	v_mfma_f32_32x32x16_bf16 v[50:65], v[108:111], v[116:119], v[50:65]
	global_load_lds_dwordx4 v146, s[74:75]
	s_add_i32 m0, s79, 0x16100
	s_waitcnt lgkmcnt(5)
	v_mfma_f32_32x32x16_bf16 v[18:33], v[108:111], v[120:123], v[18:33]
	global_load_lds_dwordx4 v147, s[74:75]
	s_waitcnt lgkmcnt(4)
	v_mfma_f32_32x32x16_bf16 v[34:49], v[112:115], v[116:119], v[34:49]
	v_mfma_f32_32x32x16_bf16 v[2:17], v[112:115], v[120:123], v[2:17]
	s_setprio 0
	s_add_u32 s72, s72, 0x80
	s_addc_u32 s73, s73, 0
	s_add_u32 s74, s74, 0x80
	s_addc_u32 s75, s75, 0
	s_waitcnt lgkmcnt(0)
	s_waitcnt vmcnt(6)
	s_barrier
	ds_read_b128 v[108:111], v216
	ds_read_b128 v[116:119], v220
	ds_read_b128 v[120:123], v220 offset:4096
	ds_read_b128 v[112:115], v216 offset:4096
	s_setprio 1
	v_mfma_f32_32x32x16_bf16 v[50:65], v[126:129], v[134:137], v[50:65]
	v_mfma_f32_32x32x16_bf16 v[18:33], v[126:129], v[138:141], v[18:33]
	v_mfma_f32_32x32x16_bf16 v[34:49], v[130:133], v[134:137], v[34:49]
	v_mfma_f32_32x32x16_bf16 v[2:17], v[130:133], v[138:141], v[2:17]
	s_setprio 0
	ds_read_b128 v[126:129], v217
	ds_read_b128 v[134:137], v221
	ds_read_b128 v[138:141], v221 offset:4096
	ds_read_b128 v[130:133], v217 offset:4096
	s_setprio 1
	s_add_i32 m0, s79, 0x1b900
	s_waitcnt lgkmcnt(6)
	v_mfma_f32_32x32x16_bf16 v[50:65], v[108:111], v[116:119], v[50:65]
	global_load_lds_dwordx4 v144, s[72:73]
	s_add_i32 m0, s79, 0x1d900
	s_waitcnt lgkmcnt(5)
	v_mfma_f32_32x32x16_bf16 v[18:33], v[108:111], v[120:123], v[18:33]
	global_load_lds_dwordx4 v145, s[72:73]
	s_waitcnt lgkmcnt(4)
	v_mfma_f32_32x32x16_bf16 v[34:49], v[112:115], v[116:119], v[34:49]
	v_mfma_f32_32x32x16_bf16 v[2:17], v[112:115], v[120:123], v[2:17]
	s_setprio 0
	ds_read_b128 v[108:111], v218
	ds_read_b128 v[116:119], v222
	ds_read_b128 v[120:123], v222 offset:4096
	ds_read_b128 v[112:115], v218 offset:4096
	s_setprio 1
	s_add_i32 m0, s79, 0x1f900
	s_waitcnt lgkmcnt(6)
	v_mfma_f32_32x32x16_bf16 v[50:65], v[126:129], v[134:137], v[50:65]
	global_load_lds_dwordx4 v144, s[74:75]
	s_add_i32 m0, s79, 0x21900
	s_waitcnt lgkmcnt(5)
	v_mfma_f32_32x32x16_bf16 v[18:33], v[126:129], v[138:141], v[18:33]
	global_load_lds_dwordx4 v145, s[74:75]
	s_waitcnt lgkmcnt(4)
	v_mfma_f32_32x32x16_bf16 v[34:49], v[130:133], v[134:137], v[34:49]
	v_mfma_f32_32x32x16_bf16 v[2:17], v[130:133], v[138:141], v[2:17]
	s_setprio 0
	ds_read_b128 v[126:129], v219
	ds_read_b128 v[134:137], v223
	ds_read_b128 v[138:141], v223 offset:4096
	ds_read_b128 v[130:133], v219 offset:4096
	s_setprio 1
	s_add_i32 m0, s79, 0x23900
	s_waitcnt lgkmcnt(6)
	v_mfma_f32_32x32x16_bf16 v[50:65], v[108:111], v[116:119], v[50:65]
	global_load_lds_dwordx4 v146, s[74:75]
	s_add_i32 m0, s79, 0x25900
	s_waitcnt lgkmcnt(5)
	v_mfma_f32_32x32x16_bf16 v[18:33], v[108:111], v[120:123], v[18:33]
	global_load_lds_dwordx4 v147, s[74:75]
	s_waitcnt lgkmcnt(4)
	v_mfma_f32_32x32x16_bf16 v[34:49], v[112:115], v[116:119], v[34:49]
	v_mfma_f32_32x32x16_bf16 v[2:17], v[112:115], v[120:123], v[2:17]
	s_setprio 0
	s_add_u32 s72, s72, 0x80
	s_addc_u32 s73, s73, 0
	s_add_u32 s74, s74, 0x80
	s_addc_u32 s75, s75, 0
	s_waitcnt lgkmcnt(0)
	s_waitcnt vmcnt(6)
	s_barrier
	ds_read_b128 v[108:111], v216 offset:49152
	ds_read_b128 v[116:119], v220 offset:49152
	ds_read_b128 v[120:123], v220 offset:53248
	ds_read_b128 v[112:115], v216 offset:53248
	s_setprio 1
	v_mfma_f32_32x32x16_bf16 v[50:65], v[126:129], v[134:137], v[50:65]
	v_mfma_f32_32x32x16_bf16 v[18:33], v[126:129], v[138:141], v[18:33]
	v_mfma_f32_32x32x16_bf16 v[34:49], v[130:133], v[134:137], v[34:49]
	v_mfma_f32_32x32x16_bf16 v[2:17], v[130:133], v[138:141], v[2:17]
	s_setprio 0
	ds_read_b128 v[126:129], v217 offset:49152
	ds_read_b128 v[134:137], v221 offset:49152
	ds_read_b128 v[138:141], v221 offset:53248
	ds_read_b128 v[130:133], v217 offset:53248
	s_setprio 1
	s_add_i32 m0, s79, 0x100
	s_waitcnt lgkmcnt(6)
	v_mfma_f32_32x32x16_bf16 v[50:65], v[108:111], v[116:119], v[50:65]
	global_load_lds_dwordx4 v144, s[72:73]
	s_add_i32 m0, s79, 0x2100
	s_waitcnt lgkmcnt(5)
	v_mfma_f32_32x32x16_bf16 v[18:33], v[108:111], v[120:123], v[18:33]
	global_load_lds_dwordx4 v145, s[72:73]
	s_waitcnt lgkmcnt(4)
	v_mfma_f32_32x32x16_bf16 v[34:49], v[112:115], v[116:119], v[34:49]
	v_mfma_f32_32x32x16_bf16 v[2:17], v[112:115], v[120:123], v[2:17]
	s_setprio 0
	ds_read_b128 v[108:111], v218 offset:49152
	ds_read_b128 v[116:119], v222 offset:49152
	ds_read_b128 v[120:123], v222 offset:53248
	ds_read_b128 v[112:115], v218 offset:53248
	s_setprio 1
	s_add_i32 m0, s79, 0x4100
	s_waitcnt lgkmcnt(6)
	v_mfma_f32_32x32x16_bf16 v[50:65], v[126:129], v[134:137], v[50:65]
	global_load_lds_dwordx4 v144, s[74:75]
	s_add_i32 m0, s79, 0x6100
	s_waitcnt lgkmcnt(5)
	v_mfma_f32_32x32x16_bf16 v[18:33], v[126:129], v[138:141], v[18:33]
	global_load_lds_dwordx4 v145, s[74:75]
	s_waitcnt lgkmcnt(4)
	v_mfma_f32_32x32x16_bf16 v[34:49], v[130:133], v[134:137], v[34:49]
	v_mfma_f32_32x32x16_bf16 v[2:17], v[130:133], v[138:141], v[2:17]
	s_setprio 0
	ds_read_b128 v[126:129], v219 offset:49152
	ds_read_b128 v[134:137], v223 offset:49152
	ds_read_b128 v[138:141], v223 offset:53248
	ds_read_b128 v[130:133], v219 offset:53248
	s_setprio 1
	s_add_i32 m0, s79, 0x8100
	s_waitcnt lgkmcnt(6)
	v_mfma_f32_32x32x16_bf16 v[50:65], v[108:111], v[116:119], v[50:65]
	global_load_lds_dwordx4 v146, s[74:75]
	s_add_i32 m0, s79, 0xa100
	s_waitcnt lgkmcnt(5)
	v_mfma_f32_32x32x16_bf16 v[18:33], v[108:111], v[120:123], v[18:33]
	global_load_lds_dwordx4 v147, s[74:75]
	s_waitcnt lgkmcnt(4)
	v_mfma_f32_32x32x16_bf16 v[34:49], v[112:115], v[116:119], v[34:49]
	v_mfma_f32_32x32x16_bf16 v[2:17], v[112:115], v[120:123], v[2:17]
	s_setprio 0
	s_add_u32 s72, s72, 0x80
	s_addc_u32 s73, s73, 0
	s_add_u32 s74, s74, 0x80
	s_addc_u32 s75, s75, 0
	s_waitcnt lgkmcnt(0)
	s_waitcnt vmcnt(6)
	s_barrier
	ds_read_b128 v[108:111], v224
	ds_read_b128 v[116:119], v228
	ds_read_b128 v[120:123], v228 offset:4096
	ds_read_b128 v[112:115], v224 offset:4096
	s_setprio 1
	v_mfma_f32_32x32x16_bf16 v[50:65], v[126:129], v[134:137], v[50:65]
	v_mfma_f32_32x32x16_bf16 v[18:33], v[126:129], v[138:141], v[18:33]
	v_mfma_f32_32x32x16_bf16 v[34:49], v[130:133], v[134:137], v[34:49]
	v_mfma_f32_32x32x16_bf16 v[2:17], v[130:133], v[138:141], v[2:17]
	s_setprio 0
	ds_read_b128 v[126:129], v225
	ds_read_b128 v[134:137], v229
	ds_read_b128 v[138:141], v229 offset:4096
	ds_read_b128 v[130:133], v225 offset:4096
	s_setprio 1
	s_add_i32 m0, s79, 0xc100
	s_waitcnt lgkmcnt(6)
	v_mfma_f32_32x32x16_bf16 v[50:65], v[108:111], v[116:119], v[50:65]
	global_load_lds_dwordx4 v144, s[72:73]
	s_add_i32 m0, s79, 0xe100
	s_waitcnt lgkmcnt(5)
	v_mfma_f32_32x32x16_bf16 v[18:33], v[108:111], v[120:123], v[18:33]
	global_load_lds_dwordx4 v145, s[72:73]
	s_waitcnt lgkmcnt(4)
	v_mfma_f32_32x32x16_bf16 v[34:49], v[112:115], v[116:119], v[34:49]
	v_mfma_f32_32x32x16_bf16 v[2:17], v[112:115], v[120:123], v[2:17]
	s_setprio 0
	ds_read_b128 v[108:111], v226
	ds_read_b128 v[116:119], v230
	ds_read_b128 v[120:123], v230 offset:4096
	ds_read_b128 v[112:115], v226 offset:4096
	s_setprio 1
	s_add_i32 m0, s79, 0x10100
	s_waitcnt lgkmcnt(6)
	v_mfma_f32_32x32x16_bf16 v[50:65], v[126:129], v[134:137], v[50:65]
	global_load_lds_dwordx4 v144, s[74:75]
	s_add_i32 m0, s79, 0x12100
	s_waitcnt lgkmcnt(5)
	v_mfma_f32_32x32x16_bf16 v[18:33], v[126:129], v[138:141], v[18:33]
	global_load_lds_dwordx4 v145, s[74:75]
	s_waitcnt lgkmcnt(4)
	v_mfma_f32_32x32x16_bf16 v[34:49], v[130:133], v[134:137], v[34:49]
	v_mfma_f32_32x32x16_bf16 v[2:17], v[130:133], v[138:141], v[2:17]
	s_setprio 0
	ds_read_b128 v[126:129], v227
	ds_read_b128 v[134:137], v231
	ds_read_b128 v[138:141], v231 offset:4096
	ds_read_b128 v[130:133], v227 offset:4096
	s_setprio 1
	s_add_i32 m0, s79, 0x14100
	s_waitcnt lgkmcnt(6)
	v_mfma_f32_32x32x16_bf16 v[50:65], v[108:111], v[116:119], v[50:65]
	global_load_lds_dwordx4 v146, s[74:75]
	s_add_i32 m0, s79, 0x16100
	s_waitcnt lgkmcnt(5)
	v_mfma_f32_32x32x16_bf16 v[18:33], v[108:111], v[120:123], v[18:33]
	global_load_lds_dwordx4 v147, s[74:75]
	s_waitcnt lgkmcnt(4)
	v_mfma_f32_32x32x16_bf16 v[34:49], v[112:115], v[116:119], v[34:49]
	v_mfma_f32_32x32x16_bf16 v[2:17], v[112:115], v[120:123], v[2:17]
	s_setprio 0
	s_add_u32 s72, s72, 0x80
	s_addc_u32 s73, s73, 0
	s_add_u32 s74, s74, 0x80
	s_addc_u32 s75, s75, 0
	s_waitcnt lgkmcnt(0)
	s_waitcnt vmcnt(6)
	s_barrier
	ds_read_b128 v[108:111], v216
	ds_read_b128 v[116:119], v220
	ds_read_b128 v[120:123], v220 offset:4096
	ds_read_b128 v[112:115], v216 offset:4096
	s_setprio 1
	v_mfma_f32_32x32x16_bf16 v[50:65], v[126:129], v[134:137], v[50:65]
	v_mfma_f32_32x32x16_bf16 v[18:33], v[126:129], v[138:141], v[18:33]
	v_mfma_f32_32x32x16_bf16 v[34:49], v[130:133], v[134:137], v[34:49]
	v_mfma_f32_32x32x16_bf16 v[2:17], v[130:133], v[138:141], v[2:17]
	s_setprio 0
	ds_read_b128 v[126:129], v217
	ds_read_b128 v[134:137], v221
	ds_read_b128 v[138:141], v221 offset:4096
	ds_read_b128 v[130:133], v217 offset:4096
	s_setprio 1
	s_add_i32 m0, s79, 0x1b900
	s_waitcnt lgkmcnt(6)
	v_mfma_f32_32x32x16_bf16 v[50:65], v[108:111], v[116:119], v[50:65]
	global_load_lds_dwordx4 v144, s[72:73]
	s_add_i32 m0, s79, 0x1d900
	s_waitcnt lgkmcnt(5)
	v_mfma_f32_32x32x16_bf16 v[18:33], v[108:111], v[120:123], v[18:33]
	global_load_lds_dwordx4 v145, s[72:73]
	s_waitcnt lgkmcnt(4)
	v_mfma_f32_32x32x16_bf16 v[34:49], v[112:115], v[116:119], v[34:49]
	v_mfma_f32_32x32x16_bf16 v[2:17], v[112:115], v[120:123], v[2:17]
	s_setprio 0
	ds_read_b128 v[108:111], v218
	ds_read_b128 v[116:119], v222
	ds_read_b128 v[120:123], v222 offset:4096
	ds_read_b128 v[112:115], v218 offset:4096
	s_setprio 1
	s_add_i32 m0, s79, 0x1f900
	s_waitcnt lgkmcnt(6)
	v_mfma_f32_32x32x16_bf16 v[50:65], v[126:129], v[134:137], v[50:65]
	global_load_lds_dwordx4 v144, s[74:75]
	s_add_i32 m0, s79, 0x21900
	s_waitcnt lgkmcnt(5)
	v_mfma_f32_32x32x16_bf16 v[18:33], v[126:129], v[138:141], v[18:33]
	global_load_lds_dwordx4 v145, s[74:75]
	s_waitcnt lgkmcnt(4)
	v_mfma_f32_32x32x16_bf16 v[34:49], v[130:133], v[134:137], v[34:49]
	v_mfma_f32_32x32x16_bf16 v[2:17], v[130:133], v[138:141], v[2:17]
	s_setprio 0
	ds_read_b128 v[126:129], v219
	ds_read_b128 v[134:137], v223
	ds_read_b128 v[138:141], v223 offset:4096
	ds_read_b128 v[130:133], v219 offset:4096
	s_setprio 1
	s_add_i32 m0, s79, 0x23900
	s_waitcnt lgkmcnt(6)
	v_mfma_f32_32x32x16_bf16 v[50:65], v[108:111], v[116:119], v[50:65]
	global_load_lds_dwordx4 v146, s[74:75]
	s_add_i32 m0, s79, 0x25900
	s_waitcnt lgkmcnt(5)
	v_mfma_f32_32x32x16_bf16 v[18:33], v[108:111], v[120:123], v[18:33]
	global_load_lds_dwordx4 v147, s[74:75]
	s_waitcnt lgkmcnt(4)
	v_mfma_f32_32x32x16_bf16 v[34:49], v[112:115], v[116:119], v[34:49]
	v_mfma_f32_32x32x16_bf16 v[2:17], v[112:115], v[120:123], v[2:17]
	s_setprio 0
	s_add_u32 s72, s72, 0x80
	s_addc_u32 s73, s73, 0
	s_add_u32 s74, s74, 0x80
	s_addc_u32 s75, s75, 0
	s_waitcnt lgkmcnt(0)
	s_waitcnt vmcnt(6)
	s_barrier
	ds_read_b128 v[108:111], v216 offset:49152
	ds_read_b128 v[116:119], v220 offset:49152
	ds_read_b128 v[120:123], v220 offset:53248
	ds_read_b128 v[112:115], v216 offset:53248
	s_setprio 1
	v_mfma_f32_32x32x16_bf16 v[50:65], v[126:129], v[134:137], v[50:65]
	v_mfma_f32_32x32x16_bf16 v[18:33], v[126:129], v[138:141], v[18:33]
	v_mfma_f32_32x32x16_bf16 v[34:49], v[130:133], v[134:137], v[34:49]
	v_mfma_f32_32x32x16_bf16 v[2:17], v[130:133], v[138:141], v[2:17]
	s_setprio 0
	ds_read_b128 v[126:129], v217 offset:49152
	ds_read_b128 v[134:137], v221 offset:49152
	ds_read_b128 v[138:141], v221 offset:53248
	ds_read_b128 v[130:133], v217 offset:53248
	s_setprio 1
	s_add_i32 m0, s79, 0x100
	s_waitcnt lgkmcnt(6)
	v_mfma_f32_32x32x16_bf16 v[50:65], v[108:111], v[116:119], v[50:65]
	global_load_lds_dwordx4 v144, s[72:73]
	s_add_i32 m0, s79, 0x2100
	s_waitcnt lgkmcnt(5)
	v_mfma_f32_32x32x16_bf16 v[18:33], v[108:111], v[120:123], v[18:33]
	global_load_lds_dwordx4 v145, s[72:73]
	s_waitcnt lgkmcnt(4)
	v_mfma_f32_32x32x16_bf16 v[34:49], v[112:115], v[116:119], v[34:49]
	v_mfma_f32_32x32x16_bf16 v[2:17], v[112:115], v[120:123], v[2:17]
	s_setprio 0
	ds_read_b128 v[108:111], v218 offset:49152
	ds_read_b128 v[116:119], v222 offset:49152
	ds_read_b128 v[120:123], v222 offset:53248
	ds_read_b128 v[112:115], v218 offset:53248
	s_setprio 1
	s_add_i32 m0, s79, 0x4100
	s_waitcnt lgkmcnt(6)
	v_mfma_f32_32x32x16_bf16 v[50:65], v[126:129], v[134:137], v[50:65]
	global_load_lds_dwordx4 v144, s[74:75]
	s_add_i32 m0, s79, 0x6100
	s_waitcnt lgkmcnt(5)
	v_mfma_f32_32x32x16_bf16 v[18:33], v[126:129], v[138:141], v[18:33]
	global_load_lds_dwordx4 v145, s[74:75]
	s_waitcnt lgkmcnt(4)
	v_mfma_f32_32x32x16_bf16 v[34:49], v[130:133], v[134:137], v[34:49]
	v_mfma_f32_32x32x16_bf16 v[2:17], v[130:133], v[138:141], v[2:17]
	s_setprio 0
	ds_read_b128 v[126:129], v219 offset:49152
	ds_read_b128 v[134:137], v223 offset:49152
	ds_read_b128 v[138:141], v223 offset:53248
	ds_read_b128 v[130:133], v219 offset:53248
	s_setprio 1
	s_add_i32 m0, s79, 0x8100
	s_waitcnt lgkmcnt(6)
	v_mfma_f32_32x32x16_bf16 v[50:65], v[108:111], v[116:119], v[50:65]
	global_load_lds_dwordx4 v146, s[74:75]
	s_add_i32 m0, s79, 0xa100
	s_waitcnt lgkmcnt(5)
	v_mfma_f32_32x32x16_bf16 v[18:33], v[108:111], v[120:123], v[18:33]
	global_load_lds_dwordx4 v147, s[74:75]
	s_waitcnt lgkmcnt(4)
	v_mfma_f32_32x32x16_bf16 v[34:49], v[112:115], v[116:119], v[34:49]
	v_mfma_f32_32x32x16_bf16 v[2:17], v[112:115], v[120:123], v[2:17]
	s_setprio 0
	s_add_u32 s72, s72, 0x80
	s_addc_u32 s73, s73, 0
	s_add_u32 s74, s74, 0x80
	s_addc_u32 s75, s75, 0
	s_waitcnt lgkmcnt(0)
	s_waitcnt vmcnt(6)
	s_barrier
	ds_read_b128 v[108:111], v224
	ds_read_b128 v[116:119], v228
	ds_read_b128 v[120:123], v228 offset:4096
	ds_read_b128 v[112:115], v224 offset:4096
	s_setprio 1
	v_mfma_f32_32x32x16_bf16 v[50:65], v[126:129], v[134:137], v[50:65]
	v_mfma_f32_32x32x16_bf16 v[18:33], v[126:129], v[138:141], v[18:33]
	v_mfma_f32_32x32x16_bf16 v[34:49], v[130:133], v[134:137], v[34:49]
	v_mfma_f32_32x32x16_bf16 v[2:17], v[130:133], v[138:141], v[2:17]
	s_setprio 0
	ds_read_b128 v[126:129], v225
	ds_read_b128 v[134:137], v229
	ds_read_b128 v[138:141], v229 offset:4096
	ds_read_b128 v[130:133], v225 offset:4096
	s_setprio 1
	s_add_i32 m0, s79, 0xc100
	s_waitcnt lgkmcnt(6)
	v_mfma_f32_32x32x16_bf16 v[50:65], v[108:111], v[116:119], v[50:65]
	global_load_lds_dwordx4 v144, s[72:73]
	s_add_i32 m0, s79, 0xe100
	s_waitcnt lgkmcnt(5)
	v_mfma_f32_32x32x16_bf16 v[18:33], v[108:111], v[120:123], v[18:33]
	global_load_lds_dwordx4 v145, s[72:73]
	s_waitcnt lgkmcnt(4)
	v_mfma_f32_32x32x16_bf16 v[34:49], v[112:115], v[116:119], v[34:49]
	v_mfma_f32_32x32x16_bf16 v[2:17], v[112:115], v[120:123], v[2:17]
	s_setprio 0
	ds_read_b128 v[108:111], v226
	ds_read_b128 v[116:119], v230
	ds_read_b128 v[120:123], v230 offset:4096
	ds_read_b128 v[112:115], v226 offset:4096
	s_setprio 1
	s_add_i32 m0, s79, 0x10100
	s_waitcnt lgkmcnt(6)
	v_mfma_f32_32x32x16_bf16 v[50:65], v[126:129], v[134:137], v[50:65]
	global_load_lds_dwordx4 v144, s[74:75]
	s_add_i32 m0, s79, 0x12100
	s_waitcnt lgkmcnt(5)
	v_mfma_f32_32x32x16_bf16 v[18:33], v[126:129], v[138:141], v[18:33]
	global_load_lds_dwordx4 v145, s[74:75]
	s_waitcnt lgkmcnt(4)
	v_mfma_f32_32x32x16_bf16 v[34:49], v[130:133], v[134:137], v[34:49]
	v_mfma_f32_32x32x16_bf16 v[2:17], v[130:133], v[138:141], v[2:17]
	s_setprio 0
	ds_read_b128 v[126:129], v227
	ds_read_b128 v[134:137], v231
	ds_read_b128 v[138:141], v231 offset:4096
	ds_read_b128 v[130:133], v227 offset:4096
	s_setprio 1
	s_add_i32 m0, s79, 0x14100
	s_waitcnt lgkmcnt(6)
	v_mfma_f32_32x32x16_bf16 v[50:65], v[108:111], v[116:119], v[50:65]
	global_load_lds_dwordx4 v146, s[74:75]
	s_add_i32 m0, s79, 0x16100
	s_waitcnt lgkmcnt(5)
	v_mfma_f32_32x32x16_bf16 v[18:33], v[108:111], v[120:123], v[18:33]
	global_load_lds_dwordx4 v147, s[74:75]
	s_waitcnt lgkmcnt(4)
	v_mfma_f32_32x32x16_bf16 v[34:49], v[112:115], v[116:119], v[34:49]
	v_mfma_f32_32x32x16_bf16 v[2:17], v[112:115], v[120:123], v[2:17]
	s_setprio 0
	s_add_u32 s72, s72, 0x80
	s_addc_u32 s73, s73, 0
	s_add_u32 s74, s74, 0x80
	s_addc_u32 s75, s75, 0
	s_waitcnt lgkmcnt(0)
	s_waitcnt vmcnt(6)
	s_barrier
	ds_read_b128 v[108:111], v216
	ds_read_b128 v[116:119], v220
	ds_read_b128 v[120:123], v220 offset:4096
	ds_read_b128 v[112:115], v216 offset:4096
	s_setprio 1
	v_mfma_f32_32x32x16_bf16 v[50:65], v[126:129], v[134:137], v[50:65]
	v_mfma_f32_32x32x16_bf16 v[18:33], v[126:129], v[138:141], v[18:33]
	v_mfma_f32_32x32x16_bf16 v[34:49], v[130:133], v[134:137], v[34:49]
	v_mfma_f32_32x32x16_bf16 v[2:17], v[130:133], v[138:141], v[2:17]
	s_setprio 0
	ds_read_b128 v[126:129], v217
	ds_read_b128 v[134:137], v221
	ds_read_b128 v[138:141], v221 offset:4096
	ds_read_b128 v[130:133], v217 offset:4096
	s_setprio 1
	s_add_i32 m0, s79, 0x1b900
	s_waitcnt lgkmcnt(6)
	v_mfma_f32_32x32x16_bf16 v[50:65], v[108:111], v[116:119], v[50:65]
	global_load_lds_dwordx4 v144, s[72:73]
	s_add_i32 m0, s79, 0x1d900
	s_waitcnt lgkmcnt(5)
	v_mfma_f32_32x32x16_bf16 v[18:33], v[108:111], v[120:123], v[18:33]
	global_load_lds_dwordx4 v145, s[72:73]
	s_waitcnt lgkmcnt(4)
	v_mfma_f32_32x32x16_bf16 v[34:49], v[112:115], v[116:119], v[34:49]
	v_mfma_f32_32x32x16_bf16 v[2:17], v[112:115], v[120:123], v[2:17]
	s_setprio 0
	ds_read_b128 v[108:111], v218
	ds_read_b128 v[116:119], v222
	ds_read_b128 v[120:123], v222 offset:4096
	ds_read_b128 v[112:115], v218 offset:4096
	s_setprio 1
	s_add_i32 m0, s79, 0x1f900
	s_waitcnt lgkmcnt(6)
	v_mfma_f32_32x32x16_bf16 v[50:65], v[126:129], v[134:137], v[50:65]
	global_load_lds_dwordx4 v144, s[74:75]
	s_add_i32 m0, s79, 0x21900
	s_waitcnt lgkmcnt(5)
	v_mfma_f32_32x32x16_bf16 v[18:33], v[126:129], v[138:141], v[18:33]
	global_load_lds_dwordx4 v145, s[74:75]
	s_waitcnt lgkmcnt(4)
	v_mfma_f32_32x32x16_bf16 v[34:49], v[130:133], v[134:137], v[34:49]
	v_mfma_f32_32x32x16_bf16 v[2:17], v[130:133], v[138:141], v[2:17]
	s_setprio 0
	ds_read_b128 v[126:129], v219
	ds_read_b128 v[134:137], v223
	ds_read_b128 v[138:141], v223 offset:4096
	ds_read_b128 v[130:133], v219 offset:4096
	s_setprio 1
	s_add_i32 m0, s79, 0x23900
	s_waitcnt lgkmcnt(6)
	v_mfma_f32_32x32x16_bf16 v[50:65], v[108:111], v[116:119], v[50:65]
	global_load_lds_dwordx4 v146, s[74:75]
	s_add_i32 m0, s79, 0x25900
	s_waitcnt lgkmcnt(5)
	v_mfma_f32_32x32x16_bf16 v[18:33], v[108:111], v[120:123], v[18:33]
	global_load_lds_dwordx4 v147, s[74:75]
	s_waitcnt lgkmcnt(4)
	v_mfma_f32_32x32x16_bf16 v[34:49], v[112:115], v[116:119], v[34:49]
	v_mfma_f32_32x32x16_bf16 v[2:17], v[112:115], v[120:123], v[2:17]
	s_setprio 0
	s_add_u32 s72, s72, 0x80
	s_addc_u32 s73, s73, 0
	s_add_u32 s74, s74, 0x80
	s_addc_u32 s75, s75, 0
	s_waitcnt lgkmcnt(0)
	s_waitcnt vmcnt(6)
	s_barrier
	ds_read_b128 v[108:111], v216 offset:49152
	ds_read_b128 v[116:119], v220 offset:49152
	ds_read_b128 v[120:123], v220 offset:53248
	ds_read_b128 v[112:115], v216 offset:53248
	s_setprio 1
	v_mfma_f32_32x32x16_bf16 v[50:65], v[126:129], v[134:137], v[50:65]
	v_mfma_f32_32x32x16_bf16 v[18:33], v[126:129], v[138:141], v[18:33]
	v_mfma_f32_32x32x16_bf16 v[34:49], v[130:133], v[134:137], v[34:49]
	v_mfma_f32_32x32x16_bf16 v[2:17], v[130:133], v[138:141], v[2:17]
	s_setprio 0
	ds_read_b128 v[126:129], v217 offset:49152
	ds_read_b128 v[134:137], v221 offset:49152
	ds_read_b128 v[138:141], v221 offset:53248
	ds_read_b128 v[130:133], v217 offset:53248
	s_setprio 1
	s_add_i32 m0, s79, 0x100
	s_waitcnt lgkmcnt(6)
	v_mfma_f32_32x32x16_bf16 v[50:65], v[108:111], v[116:119], v[50:65]
	global_load_lds_dwordx4 v144, s[72:73]
	s_add_i32 m0, s79, 0x2100
	s_waitcnt lgkmcnt(5)
	v_mfma_f32_32x32x16_bf16 v[18:33], v[108:111], v[120:123], v[18:33]
	global_load_lds_dwordx4 v145, s[72:73]
	s_waitcnt lgkmcnt(4)
	v_mfma_f32_32x32x16_bf16 v[34:49], v[112:115], v[116:119], v[34:49]
	v_mfma_f32_32x32x16_bf16 v[2:17], v[112:115], v[120:123], v[2:17]
	s_setprio 0
	ds_read_b128 v[108:111], v218 offset:49152
	ds_read_b128 v[116:119], v222 offset:49152
	ds_read_b128 v[120:123], v222 offset:53248
	ds_read_b128 v[112:115], v218 offset:53248
	s_setprio 1
	s_add_i32 m0, s79, 0x4100
	s_waitcnt lgkmcnt(6)
	v_mfma_f32_32x32x16_bf16 v[50:65], v[126:129], v[134:137], v[50:65]
	global_load_lds_dwordx4 v144, s[74:75]
	s_add_i32 m0, s79, 0x6100
	s_waitcnt lgkmcnt(5)
	v_mfma_f32_32x32x16_bf16 v[18:33], v[126:129], v[138:141], v[18:33]
	global_load_lds_dwordx4 v145, s[74:75]
	s_waitcnt lgkmcnt(4)
	v_mfma_f32_32x32x16_bf16 v[34:49], v[130:133], v[134:137], v[34:49]
	v_mfma_f32_32x32x16_bf16 v[2:17], v[130:133], v[138:141], v[2:17]
	s_setprio 0
	ds_read_b128 v[126:129], v219 offset:49152
	ds_read_b128 v[134:137], v223 offset:49152
	ds_read_b128 v[138:141], v223 offset:53248
	ds_read_b128 v[130:133], v219 offset:53248
	s_setprio 1
	s_add_i32 m0, s79, 0x8100
	s_waitcnt lgkmcnt(6)
	v_mfma_f32_32x32x16_bf16 v[50:65], v[108:111], v[116:119], v[50:65]
	global_load_lds_dwordx4 v146, s[74:75]
	s_add_i32 m0, s79, 0xa100
	s_waitcnt lgkmcnt(5)
	v_mfma_f32_32x32x16_bf16 v[18:33], v[108:111], v[120:123], v[18:33]
	global_load_lds_dwordx4 v147, s[74:75]
	s_waitcnt lgkmcnt(4)
	v_mfma_f32_32x32x16_bf16 v[34:49], v[112:115], v[116:119], v[34:49]
	v_mfma_f32_32x32x16_bf16 v[2:17], v[112:115], v[120:123], v[2:17]
	s_setprio 0
	s_add_u32 s72, s72, 0x80
	s_addc_u32 s73, s73, 0
	s_add_u32 s74, s74, 0x80
	s_addc_u32 s75, s75, 0
	s_waitcnt lgkmcnt(0)
	s_waitcnt vmcnt(6)
	s_barrier
	ds_read_b128 v[108:111], v224
	ds_read_b128 v[116:119], v228
	ds_read_b128 v[120:123], v228 offset:4096
	ds_read_b128 v[112:115], v224 offset:4096
	s_setprio 1
	v_mfma_f32_32x32x16_bf16 v[50:65], v[126:129], v[134:137], v[50:65]
	v_mfma_f32_32x32x16_bf16 v[18:33], v[126:129], v[138:141], v[18:33]
	v_mfma_f32_32x32x16_bf16 v[34:49], v[130:133], v[134:137], v[34:49]
	v_mfma_f32_32x32x16_bf16 v[2:17], v[130:133], v[138:141], v[2:17]
	s_setprio 0
	ds_read_b128 v[126:129], v225
	ds_read_b128 v[134:137], v229
	ds_read_b128 v[138:141], v229 offset:4096
	ds_read_b128 v[130:133], v225 offset:4096
	s_setprio 1
	s_add_i32 m0, s79, 0xc100
	s_waitcnt lgkmcnt(6)
	v_mfma_f32_32x32x16_bf16 v[50:65], v[108:111], v[116:119], v[50:65]
	global_load_lds_dwordx4 v144, s[72:73]
	s_add_i32 m0, s79, 0xe100
	s_waitcnt lgkmcnt(5)
	v_mfma_f32_32x32x16_bf16 v[18:33], v[108:111], v[120:123], v[18:33]
	global_load_lds_dwordx4 v145, s[72:73]
	s_waitcnt lgkmcnt(4)
	v_mfma_f32_32x32x16_bf16 v[34:49], v[112:115], v[116:119], v[34:49]
	v_mfma_f32_32x32x16_bf16 v[2:17], v[112:115], v[120:123], v[2:17]
	s_setprio 0
	ds_read_b128 v[108:111], v226
	ds_read_b128 v[116:119], v230
	ds_read_b128 v[120:123], v230 offset:4096
	ds_read_b128 v[112:115], v226 offset:4096
	s_setprio 1
	s_add_i32 m0, s79, 0x10100
	s_waitcnt lgkmcnt(6)
	v_mfma_f32_32x32x16_bf16 v[50:65], v[126:129], v[134:137], v[50:65]
	global_load_lds_dwordx4 v144, s[74:75]
	s_add_i32 m0, s79, 0x12100
	s_waitcnt lgkmcnt(5)
	v_mfma_f32_32x32x16_bf16 v[18:33], v[126:129], v[138:141], v[18:33]
	global_load_lds_dwordx4 v145, s[74:75]
	s_waitcnt lgkmcnt(4)
	v_mfma_f32_32x32x16_bf16 v[34:49], v[130:133], v[134:137], v[34:49]
	v_mfma_f32_32x32x16_bf16 v[2:17], v[130:133], v[138:141], v[2:17]
	s_setprio 0
	ds_read_b128 v[126:129], v227
	ds_read_b128 v[134:137], v231
	ds_read_b128 v[138:141], v231 offset:4096
	ds_read_b128 v[130:133], v227 offset:4096
	s_setprio 1
	s_add_i32 m0, s79, 0x14100
	s_waitcnt lgkmcnt(6)
	v_mfma_f32_32x32x16_bf16 v[50:65], v[108:111], v[116:119], v[50:65]
	global_load_lds_dwordx4 v146, s[74:75]
	s_add_i32 m0, s79, 0x16100
	s_waitcnt lgkmcnt(5)
	v_mfma_f32_32x32x16_bf16 v[18:33], v[108:111], v[120:123], v[18:33]
	global_load_lds_dwordx4 v147, s[74:75]
	s_waitcnt lgkmcnt(4)
	v_mfma_f32_32x32x16_bf16 v[34:49], v[112:115], v[116:119], v[34:49]
	v_mfma_f32_32x32x16_bf16 v[2:17], v[112:115], v[120:123], v[2:17]
	s_setprio 0
	s_add_u32 s72, s72, 0x80
	s_addc_u32 s73, s73, 0
	s_add_u32 s74, s74, 0x80
	s_addc_u32 s75, s75, 0
	s_waitcnt lgkmcnt(0)
	s_waitcnt vmcnt(6)
	s_barrier
	ds_read_b128 v[108:111], v216
	ds_read_b128 v[116:119], v220
	ds_read_b128 v[120:123], v220 offset:4096
	ds_read_b128 v[112:115], v216 offset:4096
	s_setprio 1
	v_mfma_f32_32x32x16_bf16 v[50:65], v[126:129], v[134:137], v[50:65]
	v_mfma_f32_32x32x16_bf16 v[18:33], v[126:129], v[138:141], v[18:33]
	v_mfma_f32_32x32x16_bf16 v[34:49], v[130:133], v[134:137], v[34:49]
	v_mfma_f32_32x32x16_bf16 v[2:17], v[130:133], v[138:141], v[2:17]
	s_setprio 0
	ds_read_b128 v[126:129], v217
	ds_read_b128 v[134:137], v221
	ds_read_b128 v[138:141], v221 offset:4096
	ds_read_b128 v[130:133], v217 offset:4096
	s_setprio 1
	s_add_i32 m0, s79, 0x1b900
	s_waitcnt lgkmcnt(6)
	v_mfma_f32_32x32x16_bf16 v[50:65], v[108:111], v[116:119], v[50:65]
	global_load_lds_dwordx4 v144, s[72:73]
	s_add_i32 m0, s79, 0x1d900
	s_waitcnt lgkmcnt(5)
	v_mfma_f32_32x32x16_bf16 v[18:33], v[108:111], v[120:123], v[18:33]
	global_load_lds_dwordx4 v145, s[72:73]
	s_waitcnt lgkmcnt(4)
	v_mfma_f32_32x32x16_bf16 v[34:49], v[112:115], v[116:119], v[34:49]
	v_mfma_f32_32x32x16_bf16 v[2:17], v[112:115], v[120:123], v[2:17]
	s_setprio 0
	ds_read_b128 v[108:111], v218
	ds_read_b128 v[116:119], v222
	ds_read_b128 v[120:123], v222 offset:4096
	ds_read_b128 v[112:115], v218 offset:4096
	s_setprio 1
	s_add_i32 m0, s79, 0x1f900
	s_waitcnt lgkmcnt(6)
	v_mfma_f32_32x32x16_bf16 v[50:65], v[126:129], v[134:137], v[50:65]
	global_load_lds_dwordx4 v144, s[74:75]
	s_add_i32 m0, s79, 0x21900
	s_waitcnt lgkmcnt(5)
	v_mfma_f32_32x32x16_bf16 v[18:33], v[126:129], v[138:141], v[18:33]
	global_load_lds_dwordx4 v145, s[74:75]
	s_waitcnt lgkmcnt(4)
	v_mfma_f32_32x32x16_bf16 v[34:49], v[130:133], v[134:137], v[34:49]
	v_mfma_f32_32x32x16_bf16 v[2:17], v[130:133], v[138:141], v[2:17]
	s_setprio 0
	ds_read_b128 v[126:129], v219
	ds_read_b128 v[134:137], v223
	ds_read_b128 v[138:141], v223 offset:4096
	ds_read_b128 v[130:133], v219 offset:4096
	s_setprio 1
	s_add_i32 m0, s79, 0x23900
	s_waitcnt lgkmcnt(6)
	v_mfma_f32_32x32x16_bf16 v[50:65], v[108:111], v[116:119], v[50:65]
	global_load_lds_dwordx4 v146, s[74:75]
	s_add_i32 m0, s79, 0x25900
	s_waitcnt lgkmcnt(5)
	v_mfma_f32_32x32x16_bf16 v[18:33], v[108:111], v[120:123], v[18:33]
	global_load_lds_dwordx4 v147, s[74:75]
	s_waitcnt lgkmcnt(4)
	v_mfma_f32_32x32x16_bf16 v[34:49], v[112:115], v[116:119], v[34:49]
	v_mfma_f32_32x32x16_bf16 v[2:17], v[112:115], v[120:123], v[2:17]
	s_setprio 0
	s_add_u32 s72, s72, 0x80
	s_addc_u32 s73, s73, 0
	s_add_u32 s74, s74, 0x80
	s_addc_u32 s75, s75, 0
	s_waitcnt lgkmcnt(0)
	s_waitcnt vmcnt(6)
	s_barrier
	ds_read_b128 v[108:111], v216 offset:49152
	ds_read_b128 v[116:119], v220 offset:49152
	ds_read_b128 v[120:123], v220 offset:53248
	ds_read_b128 v[112:115], v216 offset:53248
	s_setprio 1
	v_mfma_f32_32x32x16_bf16 v[50:65], v[126:129], v[134:137], v[50:65]
	v_mfma_f32_32x32x16_bf16 v[18:33], v[126:129], v[138:141], v[18:33]
	v_mfma_f32_32x32x16_bf16 v[34:49], v[130:133], v[134:137], v[34:49]
	v_mfma_f32_32x32x16_bf16 v[2:17], v[130:133], v[138:141], v[2:17]
	s_setprio 0
	ds_read_b128 v[126:129], v217 offset:49152
	ds_read_b128 v[134:137], v221 offset:49152
	ds_read_b128 v[138:141], v221 offset:53248
	ds_read_b128 v[130:133], v217 offset:53248
	s_setprio 1
	s_add_i32 m0, s79, 0x100
	s_waitcnt lgkmcnt(6)
	v_mfma_f32_32x32x16_bf16 v[50:65], v[108:111], v[116:119], v[50:65]
	global_load_lds_dwordx4 v144, s[72:73]
	s_add_i32 m0, s79, 0x2100
	s_waitcnt lgkmcnt(5)
	v_mfma_f32_32x32x16_bf16 v[18:33], v[108:111], v[120:123], v[18:33]
	global_load_lds_dwordx4 v145, s[72:73]
	s_waitcnt lgkmcnt(4)
	v_mfma_f32_32x32x16_bf16 v[34:49], v[112:115], v[116:119], v[34:49]
	v_mfma_f32_32x32x16_bf16 v[2:17], v[112:115], v[120:123], v[2:17]
	s_setprio 0
	ds_read_b128 v[108:111], v218 offset:49152
	ds_read_b128 v[116:119], v222 offset:49152
	ds_read_b128 v[120:123], v222 offset:53248
	ds_read_b128 v[112:115], v218 offset:53248
	s_setprio 1
	s_add_i32 m0, s79, 0x4100
	s_waitcnt lgkmcnt(6)
	v_mfma_f32_32x32x16_bf16 v[50:65], v[126:129], v[134:137], v[50:65]
	global_load_lds_dwordx4 v144, s[74:75]
	s_add_i32 m0, s79, 0x6100
	s_waitcnt lgkmcnt(5)
	v_mfma_f32_32x32x16_bf16 v[18:33], v[126:129], v[138:141], v[18:33]
	global_load_lds_dwordx4 v145, s[74:75]
	s_waitcnt lgkmcnt(4)
	v_mfma_f32_32x32x16_bf16 v[34:49], v[130:133], v[134:137], v[34:49]
	v_mfma_f32_32x32x16_bf16 v[2:17], v[130:133], v[138:141], v[2:17]
	s_setprio 0
	ds_read_b128 v[126:129], v219 offset:49152
	ds_read_b128 v[134:137], v223 offset:49152
	ds_read_b128 v[138:141], v223 offset:53248
	ds_read_b128 v[130:133], v219 offset:53248
	s_setprio 1
	s_add_i32 m0, s79, 0x8100
	s_waitcnt lgkmcnt(6)
	v_mfma_f32_32x32x16_bf16 v[50:65], v[108:111], v[116:119], v[50:65]
	global_load_lds_dwordx4 v146, s[74:75]
	s_add_i32 m0, s79, 0xa100
	s_waitcnt lgkmcnt(5)
	v_mfma_f32_32x32x16_bf16 v[18:33], v[108:111], v[120:123], v[18:33]
	global_load_lds_dwordx4 v147, s[74:75]
	s_waitcnt lgkmcnt(4)
	v_mfma_f32_32x32x16_bf16 v[34:49], v[112:115], v[116:119], v[34:49]
	v_mfma_f32_32x32x16_bf16 v[2:17], v[112:115], v[120:123], v[2:17]
	s_setprio 0
	s_add_u32 s72, s72, 0x80
	s_addc_u32 s73, s73, 0
	s_add_u32 s74, s74, 0x80
	s_addc_u32 s75, s75, 0
	s_waitcnt lgkmcnt(0)
	s_waitcnt vmcnt(6)
	s_barrier
	ds_read_b128 v[108:111], v224
	ds_read_b128 v[116:119], v228
	ds_read_b128 v[120:123], v228 offset:4096
	ds_read_b128 v[112:115], v224 offset:4096
	s_setprio 1
	v_mfma_f32_32x32x16_bf16 v[50:65], v[126:129], v[134:137], v[50:65]
	v_mfma_f32_32x32x16_bf16 v[18:33], v[126:129], v[138:141], v[18:33]
	v_mfma_f32_32x32x16_bf16 v[34:49], v[130:133], v[134:137], v[34:49]
	v_mfma_f32_32x32x16_bf16 v[2:17], v[130:133], v[138:141], v[2:17]
	s_setprio 0
	ds_read_b128 v[126:129], v225
	ds_read_b128 v[134:137], v229
	ds_read_b128 v[138:141], v229 offset:4096
	ds_read_b128 v[130:133], v225 offset:4096
	s_setprio 1
	s_waitcnt lgkmcnt(6)
	v_mfma_f32_32x32x16_bf16 v[50:65], v[108:111], v[116:119], v[50:65]
	s_waitcnt lgkmcnt(5)
	v_mfma_f32_32x32x16_bf16 v[18:33], v[108:111], v[120:123], v[18:33]
	s_waitcnt lgkmcnt(4)
	v_mfma_f32_32x32x16_bf16 v[34:49], v[112:115], v[116:119], v[34:49]
	v_mfma_f32_32x32x16_bf16 v[2:17], v[112:115], v[120:123], v[2:17]
	s_setprio 0
	ds_read_b128 v[108:111], v226
	ds_read_b128 v[116:119], v230
	ds_read_b128 v[120:123], v230 offset:4096
	ds_read_b128 v[112:115], v226 offset:4096
	s_setprio 1
	s_waitcnt lgkmcnt(6)
	v_mfma_f32_32x32x16_bf16 v[50:65], v[126:129], v[134:137], v[50:65]
	s_waitcnt lgkmcnt(5)
	v_mfma_f32_32x32x16_bf16 v[18:33], v[126:129], v[138:141], v[18:33]
	s_waitcnt lgkmcnt(4)
	v_mfma_f32_32x32x16_bf16 v[34:49], v[130:133], v[134:137], v[34:49]
	v_mfma_f32_32x32x16_bf16 v[2:17], v[130:133], v[138:141], v[2:17]
	s_setprio 0
	ds_read_b128 v[126:129], v227
	ds_read_b128 v[134:137], v231
	ds_read_b128 v[138:141], v231 offset:4096
	ds_read_b128 v[130:133], v227 offset:4096
	s_setprio 1
	s_waitcnt lgkmcnt(6)
	v_mfma_f32_32x32x16_bf16 v[50:65], v[108:111], v[116:119], v[50:65]
	s_waitcnt lgkmcnt(5)
	v_mfma_f32_32x32x16_bf16 v[18:33], v[108:111], v[120:123], v[18:33]
	s_waitcnt lgkmcnt(4)
	v_mfma_f32_32x32x16_bf16 v[34:49], v[112:115], v[116:119], v[34:49]
	v_mfma_f32_32x32x16_bf16 v[2:17], v[112:115], v[120:123], v[2:17]
	s_setprio 0
	s_waitcnt lgkmcnt(0)
	s_waitcnt vmcnt(0)
	s_barrier
	ds_read_b128 v[108:111], v216
	ds_read_b128 v[116:119], v220
	ds_read_b128 v[120:123], v220 offset:4096
	ds_read_b128 v[112:115], v216 offset:4096
	s_setprio 1
	v_mfma_f32_32x32x16_bf16 v[50:65], v[126:129], v[134:137], v[50:65]
	v_mfma_f32_32x32x16_bf16 v[18:33], v[126:129], v[138:141], v[18:33]
	v_mfma_f32_32x32x16_bf16 v[34:49], v[130:133], v[134:137], v[34:49]
	v_mfma_f32_32x32x16_bf16 v[2:17], v[130:133], v[138:141], v[2:17]
	s_setprio 0
	ds_read_b128 v[126:129], v217
	ds_read_b128 v[134:137], v221
	ds_read_b128 v[138:141], v221 offset:4096
	ds_read_b128 v[130:133], v217 offset:4096
	s_setprio 1
	s_waitcnt lgkmcnt(6)
	v_mfma_f32_32x32x16_bf16 v[50:65], v[108:111], v[116:119], v[50:65]
	s_waitcnt lgkmcnt(5)
	v_mfma_f32_32x32x16_bf16 v[18:33], v[108:111], v[120:123], v[18:33]
	s_waitcnt lgkmcnt(4)
	v_mfma_f32_32x32x16_bf16 v[34:49], v[112:115], v[116:119], v[34:49]
	v_mfma_f32_32x32x16_bf16 v[2:17], v[112:115], v[120:123], v[2:17]
	s_setprio 0
	ds_read_b128 v[108:111], v218
	ds_read_b128 v[116:119], v222
	ds_read_b128 v[120:123], v222 offset:4096
	ds_read_b128 v[112:115], v218 offset:4096
	s_setprio 1
	s_waitcnt lgkmcnt(6)
	v_mfma_f32_32x32x16_bf16 v[50:65], v[126:129], v[134:137], v[50:65]
	s_waitcnt lgkmcnt(5)
	v_mfma_f32_32x32x16_bf16 v[18:33], v[126:129], v[138:141], v[18:33]
	s_waitcnt lgkmcnt(4)
	v_mfma_f32_32x32x16_bf16 v[34:49], v[130:133], v[134:137], v[34:49]
	v_mfma_f32_32x32x16_bf16 v[2:17], v[130:133], v[138:141], v[2:17]
	s_setprio 0
	ds_read_b128 v[126:129], v219
	ds_read_b128 v[134:137], v223
	ds_read_b128 v[138:141], v223 offset:4096
	ds_read_b128 v[130:133], v219 offset:4096
	s_setprio 1
	s_waitcnt lgkmcnt(6)
	v_mfma_f32_32x32x16_bf16 v[50:65], v[108:111], v[116:119], v[50:65]
	s_waitcnt lgkmcnt(5)
	v_mfma_f32_32x32x16_bf16 v[18:33], v[108:111], v[120:123], v[18:33]
	s_waitcnt lgkmcnt(4)
	v_mfma_f32_32x32x16_bf16 v[34:49], v[112:115], v[116:119], v[34:49]
	v_mfma_f32_32x32x16_bf16 v[2:17], v[112:115], v[120:123], v[2:17]
	s_setprio 0
	s_waitcnt lgkmcnt(0)
	s_waitcnt vmcnt(0)
	s_barrier

.Lg2_loop:
	ds_read_b128 v[102:105], v225
	ds_read_b128 v[110:113], v229
	ds_read_b128 v[114:117], v229 offset:4096
	ds_read_b128 v[106:109], v225 offset:4096
	s_setprio 1
	s_add_i32 m0, s19, 0x1b900
	s_waitcnt lgkmcnt(6)
	v_mfma_f32_32x32x16_bf16 v[48:63], v[84:87], v[92:95], v[48:63]
	global_load_lds_dwordx4 v124, s[12:13]
	s_add_i32 m0, s19, 0x1d900
	s_waitcnt lgkmcnt(5)
	v_mfma_f32_32x32x16_bf16 v[32:47], v[84:87], v[96:99], v[32:47]
	global_load_lds_dwordx4 v125, s[12:13]
	s_waitcnt lgkmcnt(4)
	v_mfma_f32_32x32x16_bf16 v[16:31], v[88:91], v[92:95], v[16:31]
	v_mfma_f32_32x32x16_bf16 v[0:15], v[88:91], v[96:99], v[0:15]
	s_setprio 0
	ds_read_b128 v[84:87], v226
	ds_read_b128 v[92:95], v230
	ds_read_b128 v[96:99], v230 offset:4096
	ds_read_b128 v[88:91], v226 offset:4096
	s_setprio 1
	s_add_i32 m0, s19, 0x1f900
	s_waitcnt lgkmcnt(6)
	v_mfma_f32_32x32x16_bf16 v[48:63], v[102:105], v[110:113], v[48:63]
	global_load_lds_dwordx4 v124, s[14:15]
	s_add_i32 m0, s19, 0x21900
	s_waitcnt lgkmcnt(5)
	v_mfma_f32_32x32x16_bf16 v[32:47], v[102:105], v[114:117], v[32:47]
	global_load_lds_dwordx4 v125, s[14:15]
	s_waitcnt lgkmcnt(4)
	v_mfma_f32_32x32x16_bf16 v[16:31], v[106:109], v[110:113], v[16:31]
	v_mfma_f32_32x32x16_bf16 v[0:15], v[106:109], v[114:117], v[0:15]
	s_setprio 0
	ds_read_b128 v[102:105], v227
	ds_read_b128 v[110:113], v231
	ds_read_b128 v[114:117], v231 offset:4096
	ds_read_b128 v[106:109], v227 offset:4096
	s_setprio 1
	s_add_i32 m0, s19, 0x23900
	s_waitcnt lgkmcnt(6)
	v_mfma_f32_32x32x16_bf16 v[48:63], v[84:87], v[92:95], v[48:63]
	global_load_lds_dwordx4 v126, s[14:15]
	s_add_i32 m0, s19, 0x25900
	s_waitcnt lgkmcnt(5)
	v_mfma_f32_32x32x16_bf16 v[32:47], v[84:87], v[96:99], v[32:47]
	global_load_lds_dwordx4 v127, s[14:15]
	s_waitcnt lgkmcnt(4)
	v_mfma_f32_32x32x16_bf16 v[16:31], v[88:91], v[92:95], v[16:31]
	v_mfma_f32_32x32x16_bf16 v[0:15], v[88:91], v[96:99], v[0:15]
	s_setprio 0
	s_add_u32 s12, s12, 0x80
	s_addc_u32 s13, s13, 0
	s_add_u32 s14, s14, 0x80
	s_addc_u32 s15, s15, 0
	s_waitcnt lgkmcnt(0)
	s_waitcnt vmcnt(23)
	s_barrier
	ds_read_b128 v[84:87], v224 offset:49152
	ds_read_b128 v[92:95], v228 offset:49152
	ds_read_b128 v[96:99], v228 offset:53248
	ds_read_b128 v[88:91], v224 offset:53248
	s_setprio 1
	v_mfma_f32_32x32x16_bf16 v[48:63], v[102:105], v[110:113], v[48:63]
	v_mfma_f32_32x32x16_bf16 v[32:47], v[102:105], v[114:117], v[32:47]
	v_mfma_f32_32x32x16_bf16 v[16:31], v[106:109], v[110:113], v[16:31]
	v_mfma_f32_32x32x16_bf16 v[0:15], v[106:109], v[114:117], v[0:15]
	s_setprio 0
	ds_read_b128 v[102:105], v225 offset:49152
	ds_read_b128 v[110:113], v229 offset:49152
	ds_read_b128 v[114:117], v229 offset:53248
	ds_read_b128 v[106:109], v225 offset:53248
	s_setprio 1
	s_add_i32 m0, s19, 0x100
	s_waitcnt lgkmcnt(6)
	v_mfma_f32_32x32x16_bf16 v[48:63], v[84:87], v[92:95], v[48:63]
	global_load_lds_dwordx4 v124, s[12:13]
	s_add_i32 m0, s19, 0x2100
	s_waitcnt lgkmcnt(5)
	v_mfma_f32_32x32x16_bf16 v[32:47], v[84:87], v[96:99], v[32:47]
	global_load_lds_dwordx4 v125, s[12:13]
	s_waitcnt lgkmcnt(4)
	v_mfma_f32_32x32x16_bf16 v[16:31], v[88:91], v[92:95], v[16:31]
	v_mfma_f32_32x32x16_bf16 v[0:15], v[88:91], v[96:99], v[0:15]
	s_setprio 0
	ds_read_b128 v[84:87], v226 offset:49152
	ds_read_b128 v[92:95], v230 offset:49152
	ds_read_b128 v[96:99], v230 offset:53248
	ds_read_b128 v[88:91], v226 offset:53248
	s_setprio 1
	s_add_i32 m0, s19, 0x4100
	s_waitcnt lgkmcnt(6)
	v_mfma_f32_32x32x16_bf16 v[48:63], v[102:105], v[110:113], v[48:63]
	global_load_lds_dwordx4 v124, s[14:15]
	s_add_i32 m0, s19, 0x6100
	s_waitcnt lgkmcnt(5)
	v_mfma_f32_32x32x16_bf16 v[32:47], v[102:105], v[114:117], v[32:47]
	global_load_lds_dwordx4 v125, s[14:15]
	s_waitcnt lgkmcnt(4)
	v_mfma_f32_32x32x16_bf16 v[16:31], v[106:109], v[110:113], v[16:31]
	v_mfma_f32_32x32x16_bf16 v[0:15], v[106:109], v[114:117], v[0:15]
	s_setprio 0
	ds_read_b128 v[102:105], v227 offset:49152
	ds_read_b128 v[110:113], v231 offset:49152
	ds_read_b128 v[114:117], v231 offset:53248
	ds_read_b128 v[106:109], v227 offset:53248
	s_setprio 1
	s_add_i32 m0, s19, 0x8100
	s_waitcnt lgkmcnt(6)
	v_mfma_f32_32x32x16_bf16 v[48:63], v[84:87], v[92:95], v[48:63]
	global_load_lds_dwordx4 v126, s[14:15]
	s_add_i32 m0, s19, 0xa100
	s_waitcnt lgkmcnt(5)
	v_mfma_f32_32x32x16_bf16 v[32:47], v[84:87], v[96:99], v[32:47]
	global_load_lds_dwordx4 v127, s[14:15]
	s_waitcnt lgkmcnt(4)
	v_mfma_f32_32x32x16_bf16 v[16:31], v[88:91], v[92:95], v[16:31]
	v_mfma_f32_32x32x16_bf16 v[0:15], v[88:91], v[96:99], v[0:15]
	s_setprio 0
	s_add_u32 s12, s12, 0x80
	s_addc_u32 s13, s13, 0
	s_add_u32 s14, s14, 0x80
	s_addc_u32 s15, s15, 0
	s_waitcnt lgkmcnt(0)
	s_waitcnt vmcnt(6)
	s_barrier
	ds_read_b128 v[84:87], v232
	ds_read_b128 v[92:95], v236
	ds_read_b128 v[96:99], v236 offset:4096
	ds_read_b128 v[88:91], v232 offset:4096
	s_setprio 1
	v_mfma_f32_32x32x16_bf16 v[48:63], v[102:105], v[110:113], v[48:63]
	v_mfma_f32_32x32x16_bf16 v[32:47], v[102:105], v[114:117], v[32:47]
	v_mfma_f32_32x32x16_bf16 v[16:31], v[106:109], v[110:113], v[16:31]
	v_mfma_f32_32x32x16_bf16 v[0:15], v[106:109], v[114:117], v[0:15]
	s_setprio 0
	ds_read_b128 v[102:105], v233
	ds_read_b128 v[110:113], v237
	ds_read_b128 v[114:117], v237 offset:4096
	ds_read_b128 v[106:109], v233 offset:4096
	s_setprio 1
	s_add_i32 m0, s19, 0xc100
	s_waitcnt lgkmcnt(6)
	v_mfma_f32_32x32x16_bf16 v[48:63], v[84:87], v[92:95], v[48:63]
	global_load_lds_dwordx4 v124, s[12:13]
	s_add_i32 m0, s19, 0xe100
	s_waitcnt lgkmcnt(5)
	v_mfma_f32_32x32x16_bf16 v[32:47], v[84:87], v[96:99], v[32:47]
	global_load_lds_dwordx4 v125, s[12:13]
	s_waitcnt lgkmcnt(4)
	v_mfma_f32_32x32x16_bf16 v[16:31], v[88:91], v[92:95], v[16:31]
	v_mfma_f32_32x32x16_bf16 v[0:15], v[88:91], v[96:99], v[0:15]
	s_setprio 0
	ds_read_b128 v[84:87], v234
	ds_read_b128 v[92:95], v238
	ds_read_b128 v[96:99], v238 offset:4096
	ds_read_b128 v[88:91], v234 offset:4096
	s_setprio 1
	s_add_i32 m0, s19, 0x10100
	s_waitcnt lgkmcnt(6)
	v_mfma_f32_32x32x16_bf16 v[48:63], v[102:105], v[110:113], v[48:63]
	global_load_lds_dwordx4 v124, s[14:15]
	s_add_i32 m0, s19, 0x12100
	s_waitcnt lgkmcnt(5)
	v_mfma_f32_32x32x16_bf16 v[32:47], v[102:105], v[114:117], v[32:47]
	global_load_lds_dwordx4 v125, s[14:15]
	s_waitcnt lgkmcnt(4)
	v_mfma_f32_32x32x16_bf16 v[16:31], v[106:109], v[110:113], v[16:31]
	v_mfma_f32_32x32x16_bf16 v[0:15], v[106:109], v[114:117], v[0:15]
	s_setprio 0
	ds_read_b128 v[102:105], v235
	ds_read_b128 v[110:113], v239
	ds_read_b128 v[114:117], v239 offset:4096
	ds_read_b128 v[106:109], v235 offset:4096
	s_setprio 1
	s_add_i32 m0, s19, 0x14100
	s_waitcnt lgkmcnt(6)
	v_mfma_f32_32x32x16_bf16 v[48:63], v[84:87], v[92:95], v[48:63]
	global_load_lds_dwordx4 v126, s[14:15]
	s_add_i32 m0, s19, 0x16100
	s_waitcnt lgkmcnt(5)
	v_mfma_f32_32x32x16_bf16 v[32:47], v[84:87], v[96:99], v[32:47]
	global_load_lds_dwordx4 v127, s[14:15]
	s_waitcnt lgkmcnt(4)
	v_mfma_f32_32x32x16_bf16 v[16:31], v[88:91], v[92:95], v[16:31]
	v_mfma_f32_32x32x16_bf16 v[0:15], v[88:91], v[96:99], v[0:15]
	s_setprio 0
	s_add_u32 s12, s12, 0x80
	s_addc_u32 s13, s13, 0
	s_add_u32 s14, s14, 0x80
	s_addc_u32 s15, s15, 0
	s_waitcnt lgkmcnt(0)
	s_waitcnt vmcnt(6)
	s_barrier
	ds_read_b128 v[84:87], v224
	ds_read_b128 v[92:95], v228
	ds_read_b128 v[96:99], v228 offset:4096
	ds_read_b128 v[88:91], v224 offset:4096
	s_setprio 1
	v_mfma_f32_32x32x16_bf16 v[48:63], v[102:105], v[110:113], v[48:63]
	v_mfma_f32_32x32x16_bf16 v[32:47], v[102:105], v[114:117], v[32:47]
	v_mfma_f32_32x32x16_bf16 v[16:31], v[106:109], v[110:113], v[16:31]
	v_mfma_f32_32x32x16_bf16 v[0:15], v[106:109], v[114:117], v[0:15]
	s_setprio 0
	ds_read_b128 v[102:105], v225
	ds_read_b128 v[110:113], v229
	ds_read_b128 v[114:117], v229 offset:4096
	ds_read_b128 v[106:109], v225 offset:4096
	s_setprio 1
	s_add_i32 m0, s19, 0x1b900
	s_waitcnt lgkmcnt(6)
	v_mfma_f32_32x32x16_bf16 v[48:63], v[84:87], v[92:95], v[48:63]
	global_load_lds_dwordx4 v124, s[12:13]
	s_add_i32 m0, s19, 0x1d900
	s_waitcnt lgkmcnt(5)
	v_mfma_f32_32x32x16_bf16 v[32:47], v[84:87], v[96:99], v[32:47]
	global_load_lds_dwordx4 v125, s[12:13]
	s_waitcnt lgkmcnt(4)
	v_mfma_f32_32x32x16_bf16 v[16:31], v[88:91], v[92:95], v[16:31]
	v_mfma_f32_32x32x16_bf16 v[0:15], v[88:91], v[96:99], v[0:15]
	s_setprio 0
	ds_read_b128 v[84:87], v226
	ds_read_b128 v[92:95], v230
	ds_read_b128 v[96:99], v230 offset:4096
	ds_read_b128 v[88:91], v226 offset:4096
	s_setprio 1
	s_add_i32 m0, s19, 0x1f900
	s_waitcnt lgkmcnt(6)
	v_mfma_f32_32x32x16_bf16 v[48:63], v[102:105], v[110:113], v[48:63]
	global_load_lds_dwordx4 v124, s[14:15]
	s_add_i32 m0, s19, 0x21900
	s_waitcnt lgkmcnt(5)
	v_mfma_f32_32x32x16_bf16 v[32:47], v[102:105], v[114:117], v[32:47]
	global_load_lds_dwordx4 v125, s[14:15]
	s_waitcnt lgkmcnt(4)
	v_mfma_f32_32x32x16_bf16 v[16:31], v[106:109], v[110:113], v[16:31]
	v_mfma_f32_32x32x16_bf16 v[0:15], v[106:109], v[114:117], v[0:15]
	s_setprio 0
	ds_read_b128 v[102:105], v227
	ds_read_b128 v[110:113], v231
	ds_read_b128 v[114:117], v231 offset:4096
	ds_read_b128 v[106:109], v227 offset:4096
	s_setprio 1
	s_add_i32 m0, s19, 0x23900
	s_waitcnt lgkmcnt(6)
	v_mfma_f32_32x32x16_bf16 v[48:63], v[84:87], v[92:95], v[48:63]
	global_load_lds_dwordx4 v126, s[14:15]
	s_add_i32 m0, s19, 0x25900
	s_waitcnt lgkmcnt(5)
	v_mfma_f32_32x32x16_bf16 v[32:47], v[84:87], v[96:99], v[32:47]
	global_load_lds_dwordx4 v127, s[14:15]
	s_waitcnt lgkmcnt(4)
	v_mfma_f32_32x32x16_bf16 v[16:31], v[88:91], v[92:95], v[16:31]
	v_mfma_f32_32x32x16_bf16 v[0:15], v[88:91], v[96:99], v[0:15]
	s_setprio 0
	s_add_u32 s12, s12, 0x80
	s_addc_u32 s13, s13, 0
	s_add_u32 s14, s14, 0x80
	s_addc_u32 s15, s15, 0
	s_waitcnt lgkmcnt(0)
	s_waitcnt vmcnt(6)
	s_barrier
	ds_read_b128 v[84:87], v224 offset:49152
	ds_read_b128 v[92:95], v228 offset:49152
	ds_read_b128 v[96:99], v228 offset:53248
	ds_read_b128 v[88:91], v224 offset:53248
	s_setprio 1
	v_mfma_f32_32x32x16_bf16 v[48:63], v[102:105], v[110:113], v[48:63]
	v_mfma_f32_32x32x16_bf16 v[32:47], v[102:105], v[114:117], v[32:47]
	v_mfma_f32_32x32x16_bf16 v[16:31], v[106:109], v[110:113], v[16:31]
	v_mfma_f32_32x32x16_bf16 v[0:15], v[106:109], v[114:117], v[0:15]
	s_setprio 0
	ds_read_b128 v[102:105], v225 offset:49152
	ds_read_b128 v[110:113], v229 offset:49152
	ds_read_b128 v[114:117], v229 offset:53248
	ds_read_b128 v[106:109], v225 offset:53248
	s_setprio 1
	s_add_i32 m0, s19, 0x100
	s_waitcnt lgkmcnt(6)
	v_mfma_f32_32x32x16_bf16 v[48:63], v[84:87], v[92:95], v[48:63]
	global_load_lds_dwordx4 v124, s[12:13]
	s_add_i32 m0, s19, 0x2100
	s_waitcnt lgkmcnt(5)
	v_mfma_f32_32x32x16_bf16 v[32:47], v[84:87], v[96:99], v[32:47]
	global_load_lds_dwordx4 v125, s[12:13]
	s_waitcnt lgkmcnt(4)
	v_mfma_f32_32x32x16_bf16 v[16:31], v[88:91], v[92:95], v[16:31]
	v_mfma_f32_32x32x16_bf16 v[0:15], v[88:91], v[96:99], v[0:15]
	s_setprio 0
	ds_read_b128 v[84:87], v226 offset:49152
	ds_read_b128 v[92:95], v230 offset:49152
	ds_read_b128 v[96:99], v230 offset:53248
	ds_read_b128 v[88:91], v226 offset:53248
	s_setprio 1
	s_add_i32 m0, s19, 0x4100
	s_waitcnt lgkmcnt(6)
	v_mfma_f32_32x32x16_bf16 v[48:63], v[102:105], v[110:113], v[48:63]
	global_load_lds_dwordx4 v124, s[14:15]
	s_add_i32 m0, s19, 0x6100
	s_waitcnt lgkmcnt(5)
	v_mfma_f32_32x32x16_bf16 v[32:47], v[102:105], v[114:117], v[32:47]
	global_load_lds_dwordx4 v125, s[14:15]
	s_waitcnt lgkmcnt(4)
	v_mfma_f32_32x32x16_bf16 v[16:31], v[106:109], v[110:113], v[16:31]
	v_mfma_f32_32x32x16_bf16 v[0:15], v[106:109], v[114:117], v[0:15]
	s_setprio 0
	ds_read_b128 v[102:105], v227 offset:49152
	ds_read_b128 v[110:113], v231 offset:49152
	ds_read_b128 v[114:117], v231 offset:53248
	ds_read_b128 v[106:109], v227 offset:53248
	s_setprio 1
	s_add_i32 m0, s19, 0x8100
	s_waitcnt lgkmcnt(6)
	v_mfma_f32_32x32x16_bf16 v[48:63], v[84:87], v[92:95], v[48:63]
	global_load_lds_dwordx4 v126, s[14:15]
	s_add_i32 m0, s19, 0xa100
	s_waitcnt lgkmcnt(5)
	v_mfma_f32_32x32x16_bf16 v[32:47], v[84:87], v[96:99], v[32:47]
	global_load_lds_dwordx4 v127, s[14:15]
	s_waitcnt lgkmcnt(4)
	v_mfma_f32_32x32x16_bf16 v[16:31], v[88:91], v[92:95], v[16:31]
	v_mfma_f32_32x32x16_bf16 v[0:15], v[88:91], v[96:99], v[0:15]
	s_setprio 0
	s_add_u32 s12, s12, 0x80
	s_addc_u32 s13, s13, 0
	s_add_u32 s14, s14, 0x80
	s_addc_u32 s15, s15, 0
	s_waitcnt lgkmcnt(0)
	s_waitcnt vmcnt(6)
	s_barrier
	ds_read_b128 v[84:87], v232
	ds_read_b128 v[92:95], v236
	ds_read_b128 v[96:99], v236 offset:4096
	ds_read_b128 v[88:91], v232 offset:4096
	s_setprio 1
	v_mfma_f32_32x32x16_bf16 v[48:63], v[102:105], v[110:113], v[48:63]
	v_mfma_f32_32x32x16_bf16 v[32:47], v[102:105], v[114:117], v[32:47]
	v_mfma_f32_32x32x16_bf16 v[16:31], v[106:109], v[110:113], v[16:31]
	v_mfma_f32_32x32x16_bf16 v[0:15], v[106:109], v[114:117], v[0:15]
	s_setprio 0
	ds_read_b128 v[102:105], v233
	ds_read_b128 v[110:113], v237
	ds_read_b128 v[114:117], v237 offset:4096
	ds_read_b128 v[106:109], v233 offset:4096
	s_setprio 1
	s_add_i32 m0, s19, 0xc100
	s_waitcnt lgkmcnt(6)
	v_mfma_f32_32x32x16_bf16 v[48:63], v[84:87], v[92:95], v[48:63]
	global_load_lds_dwordx4 v124, s[12:13]
	s_add_i32 m0, s19, 0xe100
	s_waitcnt lgkmcnt(5)
	v_mfma_f32_32x32x16_bf16 v[32:47], v[84:87], v[96:99], v[32:47]
	global_load_lds_dwordx4 v125, s[12:13]
	s_waitcnt lgkmcnt(4)
	v_mfma_f32_32x32x16_bf16 v[16:31], v[88:91], v[92:95], v[16:31]
	v_mfma_f32_32x32x16_bf16 v[0:15], v[88:91], v[96:99], v[0:15]
	s_setprio 0
	ds_read_b128 v[84:87], v234
	ds_read_b128 v[92:95], v238
	ds_read_b128 v[96:99], v238 offset:4096
	ds_read_b128 v[88:91], v234 offset:4096
	s_setprio 1
	s_add_i32 m0, s19, 0x10100
	s_waitcnt lgkmcnt(6)
	v_mfma_f32_32x32x16_bf16 v[48:63], v[102:105], v[110:113], v[48:63]
	global_load_lds_dwordx4 v124, s[14:15]
	s_add_i32 m0, s19, 0x12100
	s_waitcnt lgkmcnt(5)
	v_mfma_f32_32x32x16_bf16 v[32:47], v[102:105], v[114:117], v[32:47]
	global_load_lds_dwordx4 v125, s[14:15]
	s_waitcnt lgkmcnt(4)
	v_mfma_f32_32x32x16_bf16 v[16:31], v[106:109], v[110:113], v[16:31]
	v_mfma_f32_32x32x16_bf16 v[0:15], v[106:109], v[114:117], v[0:15]
	s_setprio 0
	ds_read_b128 v[102:105], v235
	ds_read_b128 v[110:113], v239
	ds_read_b128 v[114:117], v239 offset:4096
	ds_read_b128 v[106:109], v235 offset:4096
	s_setprio 1
	s_add_i32 m0, s19, 0x14100
	s_waitcnt lgkmcnt(6)
	v_mfma_f32_32x32x16_bf16 v[48:63], v[84:87], v[92:95], v[48:63]
	global_load_lds_dwordx4 v126, s[14:15]
	s_add_i32 m0, s19, 0x16100
	s_waitcnt lgkmcnt(5)
	v_mfma_f32_32x32x16_bf16 v[32:47], v[84:87], v[96:99], v[32:47]
	global_load_lds_dwordx4 v127, s[14:15]
	s_waitcnt lgkmcnt(4)
	v_mfma_f32_32x32x16_bf16 v[16:31], v[88:91], v[92:95], v[16:31]
	v_mfma_f32_32x32x16_bf16 v[0:15], v[88:91], v[96:99], v[0:15]
	s_setprio 0
	s_add_u32 s12, s12, 0x80
	s_addc_u32 s13, s13, 0
	s_add_u32 s14, s14, 0x80
	s_addc_u32 s15, s15, 0
	s_waitcnt lgkmcnt(0)
	s_waitcnt vmcnt(6)
	s_barrier
	ds_read_b128 v[84:87], v224
	ds_read_b128 v[92:95], v228
	ds_read_b128 v[96:99], v228 offset:4096
	ds_read_b128 v[88:91], v224 offset:4096
	s_setprio 1
	v_mfma_f32_32x32x16_bf16 v[48:63], v[102:105], v[110:113], v[48:63]
	v_mfma_f32_32x32x16_bf16 v[32:47], v[102:105], v[114:117], v[32:47]
	v_mfma_f32_32x32x16_bf16 v[16:31], v[106:109], v[110:113], v[16:31]
	v_mfma_f32_32x32x16_bf16 v[0:15], v[106:109], v[114:117], v[0:15]
	s_setprio 0
	ds_read_b128 v[102:105], v225
	ds_read_b128 v[110:113], v229
	ds_read_b128 v[114:117], v229 offset:4096
	ds_read_b128 v[106:109], v225 offset:4096
	s_setprio 1
	s_add_i32 m0, s19, 0x1b900
	s_waitcnt lgkmcnt(6)
	v_mfma_f32_32x32x16_bf16 v[48:63], v[84:87], v[92:95], v[48:63]
	global_load_lds_dwordx4 v124, s[12:13]
	s_add_i32 m0, s19, 0x1d900
	s_waitcnt lgkmcnt(5)
	v_mfma_f32_32x32x16_bf16 v[32:47], v[84:87], v[96:99], v[32:47]
	global_load_lds_dwordx4 v125, s[12:13]
	s_waitcnt lgkmcnt(4)
	v_mfma_f32_32x32x16_bf16 v[16:31], v[88:91], v[92:95], v[16:31]
	v_mfma_f32_32x32x16_bf16 v[0:15], v[88:91], v[96:99], v[0:15]
	s_setprio 0
	ds_read_b128 v[84:87], v226
	ds_read_b128 v[92:95], v230
	ds_read_b128 v[96:99], v230 offset:4096
	ds_read_b128 v[88:91], v226 offset:4096
	s_setprio 1
	s_add_i32 m0, s19, 0x1f900
	s_waitcnt lgkmcnt(6)
	v_mfma_f32_32x32x16_bf16 v[48:63], v[102:105], v[110:113], v[48:63]
	global_load_lds_dwordx4 v124, s[14:15]
	s_add_i32 m0, s19, 0x21900
	s_waitcnt lgkmcnt(5)
	v_mfma_f32_32x32x16_bf16 v[32:47], v[102:105], v[114:117], v[32:47]
	global_load_lds_dwordx4 v125, s[14:15]
	s_waitcnt lgkmcnt(4)
	v_mfma_f32_32x32x16_bf16 v[16:31], v[106:109], v[110:113], v[16:31]
	v_mfma_f32_32x32x16_bf16 v[0:15], v[106:109], v[114:117], v[0:15]
	s_setprio 0
	ds_read_b128 v[102:105], v227
	ds_read_b128 v[110:113], v231
	ds_read_b128 v[114:117], v231 offset:4096
	ds_read_b128 v[106:109], v227 offset:4096
	s_setprio 1
	s_add_i32 m0, s19, 0x23900
	s_waitcnt lgkmcnt(6)
	v_mfma_f32_32x32x16_bf16 v[48:63], v[84:87], v[92:95], v[48:63]
	global_load_lds_dwordx4 v126, s[14:15]
	s_add_i32 m0, s19, 0x25900
	s_waitcnt lgkmcnt(5)
	v_mfma_f32_32x32x16_bf16 v[32:47], v[84:87], v[96:99], v[32:47]
	global_load_lds_dwordx4 v127, s[14:15]
	s_waitcnt lgkmcnt(4)
	v_mfma_f32_32x32x16_bf16 v[16:31], v[88:91], v[92:95], v[16:31]
	v_mfma_f32_32x32x16_bf16 v[0:15], v[88:91], v[96:99], v[0:15]
	s_setprio 0
	s_add_u32 s12, s12, 0x80
	s_addc_u32 s13, s13, 0
	s_add_u32 s14, s14, 0x80
	s_addc_u32 s15, s15, 0
	s_waitcnt lgkmcnt(0)
	s_waitcnt vmcnt(6)
	s_barrier
	ds_read_b128 v[84:87], v224 offset:49152
	ds_read_b128 v[92:95], v228 offset:49152
	ds_read_b128 v[96:99], v228 offset:53248
	ds_read_b128 v[88:91], v224 offset:53248
	s_setprio 1
	v_mfma_f32_32x32x16_bf16 v[48:63], v[102:105], v[110:113], v[48:63]
	v_mfma_f32_32x32x16_bf16 v[32:47], v[102:105], v[114:117], v[32:47]
	v_mfma_f32_32x32x16_bf16 v[16:31], v[106:109], v[110:113], v[16:31]
	v_mfma_f32_32x32x16_bf16 v[0:15], v[106:109], v[114:117], v[0:15]
	s_setprio 0
	ds_read_b128 v[102:105], v225 offset:49152
	ds_read_b128 v[110:113], v229 offset:49152
	ds_read_b128 v[114:117], v229 offset:53248
	ds_read_b128 v[106:109], v225 offset:53248
	s_setprio 1
	s_add_i32 m0, s19, 0x100
	s_waitcnt lgkmcnt(6)
	v_mfma_f32_32x32x16_bf16 v[48:63], v[84:87], v[92:95], v[48:63]
	global_load_lds_dwordx4 v124, s[12:13]
	s_add_i32 m0, s19, 0x2100
	s_waitcnt lgkmcnt(5)
	v_mfma_f32_32x32x16_bf16 v[32:47], v[84:87], v[96:99], v[32:47]
	global_load_lds_dwordx4 v125, s[12:13]
	s_waitcnt lgkmcnt(4)
	v_mfma_f32_32x32x16_bf16 v[16:31], v[88:91], v[92:95], v[16:31]
	v_mfma_f32_32x32x16_bf16 v[0:15], v[88:91], v[96:99], v[0:15]
	s_setprio 0
	ds_read_b128 v[84:87], v226 offset:49152
	ds_read_b128 v[92:95], v230 offset:49152
	ds_read_b128 v[96:99], v230 offset:53248
	ds_read_b128 v[88:91], v226 offset:53248
	s_setprio 1
	s_add_i32 m0, s19, 0x4100
	s_waitcnt lgkmcnt(6)
	v_mfma_f32_32x32x16_bf16 v[48:63], v[102:105], v[110:113], v[48:63]
	global_load_lds_dwordx4 v124, s[14:15]
	s_add_i32 m0, s19, 0x6100
	s_waitcnt lgkmcnt(5)
	v_mfma_f32_32x32x16_bf16 v[32:47], v[102:105], v[114:117], v[32:47]
	global_load_lds_dwordx4 v125, s[14:15]
	s_waitcnt lgkmcnt(4)
	v_mfma_f32_32x32x16_bf16 v[16:31], v[106:109], v[110:113], v[16:31]
	v_mfma_f32_32x32x16_bf16 v[0:15], v[106:109], v[114:117], v[0:15]
	s_setprio 0
	ds_read_b128 v[102:105], v227 offset:49152
	ds_read_b128 v[110:113], v231 offset:49152
	ds_read_b128 v[114:117], v231 offset:53248
	ds_read_b128 v[106:109], v227 offset:53248
	s_setprio 1
	s_add_i32 m0, s19, 0x8100
	s_waitcnt lgkmcnt(6)
	v_mfma_f32_32x32x16_bf16 v[48:63], v[84:87], v[92:95], v[48:63]
	global_load_lds_dwordx4 v126, s[14:15]
	s_add_i32 m0, s19, 0xa100
	s_waitcnt lgkmcnt(5)
	v_mfma_f32_32x32x16_bf16 v[32:47], v[84:87], v[96:99], v[32:47]
	global_load_lds_dwordx4 v127, s[14:15]
	s_waitcnt lgkmcnt(4)
	v_mfma_f32_32x32x16_bf16 v[16:31], v[88:91], v[92:95], v[16:31]
	v_mfma_f32_32x32x16_bf16 v[0:15], v[88:91], v[96:99], v[0:15]
	s_setprio 0
	s_add_u32 s12, s12, 0x80
	s_addc_u32 s13, s13, 0
	s_add_u32 s14, s14, 0x80
	s_addc_u32 s15, s15, 0
	s_waitcnt lgkmcnt(0)
	s_waitcnt vmcnt(6)
	s_barrier
	ds_read_b128 v[84:87], v232
	ds_read_b128 v[92:95], v236
	ds_read_b128 v[96:99], v236 offset:4096
	ds_read_b128 v[88:91], v232 offset:4096
	s_setprio 1
	v_mfma_f32_32x32x16_bf16 v[48:63], v[102:105], v[110:113], v[48:63]
	v_mfma_f32_32x32x16_bf16 v[32:47], v[102:105], v[114:117], v[32:47]
	v_mfma_f32_32x32x16_bf16 v[16:31], v[106:109], v[110:113], v[16:31]
	v_mfma_f32_32x32x16_bf16 v[0:15], v[106:109], v[114:117], v[0:15]
	s_setprio 0
	ds_read_b128 v[102:105], v233
	ds_read_b128 v[110:113], v237
	ds_read_b128 v[114:117], v237 offset:4096
	ds_read_b128 v[106:109], v233 offset:4096
	s_setprio 1
	s_add_i32 m0, s19, 0xc100
	s_waitcnt lgkmcnt(6)
	v_mfma_f32_32x32x16_bf16 v[48:63], v[84:87], v[92:95], v[48:63]
	global_load_lds_dwordx4 v124, s[12:13]
	s_add_i32 m0, s19, 0xe100
	s_waitcnt lgkmcnt(5)
	v_mfma_f32_32x32x16_bf16 v[32:47], v[84:87], v[96:99], v[32:47]
	global_load_lds_dwordx4 v125, s[12:13]
	s_waitcnt lgkmcnt(4)
	v_mfma_f32_32x32x16_bf16 v[16:31], v[88:91], v[92:95], v[16:31]
	v_mfma_f32_32x32x16_bf16 v[0:15], v[88:91], v[96:99], v[0:15]
	s_setprio 0
	ds_read_b128 v[84:87], v234
	ds_read_b128 v[92:95], v238
	ds_read_b128 v[96:99], v238 offset:4096
	ds_read_b128 v[88:91], v234 offset:4096
	s_setprio 1
	s_add_i32 m0, s19, 0x10100
	s_waitcnt lgkmcnt(6)
	v_mfma_f32_32x32x16_bf16 v[48:63], v[102:105], v[110:113], v[48:63]
	global_load_lds_dwordx4 v124, s[14:15]
	s_add_i32 m0, s19, 0x12100
	s_waitcnt lgkmcnt(5)
	v_mfma_f32_32x32x16_bf16 v[32:47], v[102:105], v[114:117], v[32:47]
	global_load_lds_dwordx4 v125, s[14:15]
	s_waitcnt lgkmcnt(4)
	v_mfma_f32_32x32x16_bf16 v[16:31], v[106:109], v[110:113], v[16:31]
	v_mfma_f32_32x32x16_bf16 v[0:15], v[106:109], v[114:117], v[0:15]
	s_setprio 0
	ds_read_b128 v[102:105], v235
	ds_read_b128 v[110:113], v239
	ds_read_b128 v[114:117], v239 offset:4096
	ds_read_b128 v[106:109], v235 offset:4096
	s_setprio 1
	s_add_i32 m0, s19, 0x14100
	s_waitcnt lgkmcnt(6)
	v_mfma_f32_32x32x16_bf16 v[48:63], v[84:87], v[92:95], v[48:63]
	global_load_lds_dwordx4 v126, s[14:15]
	s_add_i32 m0, s19, 0x16100
	s_waitcnt lgkmcnt(5)
	v_mfma_f32_32x32x16_bf16 v[32:47], v[84:87], v[96:99], v[32:47]
	global_load_lds_dwordx4 v127, s[14:15]
	s_waitcnt lgkmcnt(4)
	v_mfma_f32_32x32x16_bf16 v[16:31], v[88:91], v[92:95], v[16:31]
	v_mfma_f32_32x32x16_bf16 v[0:15], v[88:91], v[96:99], v[0:15]
	s_setprio 0
	s_add_u32 s12, s12, 0x80
	s_addc_u32 s13, s13, 0
	s_add_u32 s14, s14, 0x80
	s_addc_u32 s15, s15, 0
	s_waitcnt lgkmcnt(0)
	s_waitcnt vmcnt(6)
	s_barrier
	ds_read_b128 v[84:87], v224
	ds_read_b128 v[92:95], v228
	ds_read_b128 v[96:99], v228 offset:4096
	ds_read_b128 v[88:91], v224 offset:4096
	s_setprio 1
	v_mfma_f32_32x32x16_bf16 v[48:63], v[102:105], v[110:113], v[48:63]
	v_mfma_f32_32x32x16_bf16 v[32:47], v[102:105], v[114:117], v[32:47]
	v_mfma_f32_32x32x16_bf16 v[16:31], v[106:109], v[110:113], v[16:31]
	v_mfma_f32_32x32x16_bf16 v[0:15], v[106:109], v[114:117], v[0:15]
	s_setprio 0
	ds_read_b128 v[102:105], v225
	ds_read_b128 v[110:113], v229
	ds_read_b128 v[114:117], v229 offset:4096
	ds_read_b128 v[106:109], v225 offset:4096
	s_setprio 1
	s_add_i32 m0, s19, 0x1b900
	s_waitcnt lgkmcnt(6)
	v_mfma_f32_32x32x16_bf16 v[48:63], v[84:87], v[92:95], v[48:63]
	global_load_lds_dwordx4 v124, s[12:13]
	s_add_i32 m0, s19, 0x1d900
	s_waitcnt lgkmcnt(5)
	v_mfma_f32_32x32x16_bf16 v[32:47], v[84:87], v[96:99], v[32:47]
	global_load_lds_dwordx4 v125, s[12:13]
	s_waitcnt lgkmcnt(4)
	v_mfma_f32_32x32x16_bf16 v[16:31], v[88:91], v[92:95], v[16:31]
	v_mfma_f32_32x32x16_bf16 v[0:15], v[88:91], v[96:99], v[0:15]
	s_setprio 0
	ds_read_b128 v[84:87], v226
	ds_read_b128 v[92:95], v230
	ds_read_b128 v[96:99], v230 offset:4096
	ds_read_b128 v[88:91], v226 offset:4096
	s_setprio 1
	s_add_i32 m0, s19, 0x1f900
	s_waitcnt lgkmcnt(6)
	v_mfma_f32_32x32x16_bf16 v[48:63], v[102:105], v[110:113], v[48:63]
	global_load_lds_dwordx4 v124, s[14:15]
	s_add_i32 m0, s19, 0x21900
	s_waitcnt lgkmcnt(5)
	v_mfma_f32_32x32x16_bf16 v[32:47], v[102:105], v[114:117], v[32:47]
	global_load_lds_dwordx4 v125, s[14:15]
	s_waitcnt lgkmcnt(4)
	v_mfma_f32_32x32x16_bf16 v[16:31], v[106:109], v[110:113], v[16:31]
	v_mfma_f32_32x32x16_bf16 v[0:15], v[106:109], v[114:117], v[0:15]
	s_setprio 0
	ds_read_b128 v[102:105], v227
	ds_read_b128 v[110:113], v231
	ds_read_b128 v[114:117], v231 offset:4096
	ds_read_b128 v[106:109], v227 offset:4096
	s_setprio 1
	s_add_i32 m0, s19, 0x23900
	s_waitcnt lgkmcnt(6)
	v_mfma_f32_32x32x16_bf16 v[48:63], v[84:87], v[92:95], v[48:63]
	global_load_lds_dwordx4 v126, s[14:15]
	s_add_i32 m0, s19, 0x25900
	s_waitcnt lgkmcnt(5)
	v_mfma_f32_32x32x16_bf16 v[32:47], v[84:87], v[96:99], v[32:47]
	global_load_lds_dwordx4 v127, s[14:15]
	s_waitcnt lgkmcnt(4)
	v_mfma_f32_32x32x16_bf16 v[16:31], v[88:91], v[92:95], v[16:31]
	v_mfma_f32_32x32x16_bf16 v[0:15], v[88:91], v[96:99], v[0:15]
	s_setprio 0
	s_add_u32 s12, s12, 0x80
	s_addc_u32 s13, s13, 0
	s_add_u32 s14, s14, 0x80
	s_addc_u32 s15, s15, 0
	s_waitcnt lgkmcnt(0)
	s_waitcnt vmcnt(6)
	s_barrier
	ds_read_b128 v[84:87], v224 offset:49152
	ds_read_b128 v[92:95], v228 offset:49152
	ds_read_b128 v[96:99], v228 offset:53248
	ds_read_b128 v[88:91], v224 offset:53248
	s_setprio 1
	v_mfma_f32_32x32x16_bf16 v[48:63], v[102:105], v[110:113], v[48:63]
	v_mfma_f32_32x32x16_bf16 v[32:47], v[102:105], v[114:117], v[32:47]
	v_mfma_f32_32x32x16_bf16 v[16:31], v[106:109], v[110:113], v[16:31]
	v_mfma_f32_32x32x16_bf16 v[0:15], v[106:109], v[114:117], v[0:15]
	s_setprio 0
	ds_read_b128 v[102:105], v225 offset:49152
	ds_read_b128 v[110:113], v229 offset:49152
	ds_read_b128 v[114:117], v229 offset:53248
	ds_read_b128 v[106:109], v225 offset:53248
	s_setprio 1
	s_add_i32 m0, s19, 0x100
	s_waitcnt lgkmcnt(6)
	v_mfma_f32_32x32x16_bf16 v[48:63], v[84:87], v[92:95], v[48:63]
	global_load_lds_dwordx4 v124, s[12:13]
	s_add_i32 m0, s19, 0x2100
	s_waitcnt lgkmcnt(5)
	v_mfma_f32_32x32x16_bf16 v[32:47], v[84:87], v[96:99], v[32:47]
	global_load_lds_dwordx4 v125, s[12:13]
	s_waitcnt lgkmcnt(4)
	v_mfma_f32_32x32x16_bf16 v[16:31], v[88:91], v[92:95], v[16:31]
	v_mfma_f32_32x32x16_bf16 v[0:15], v[88:91], v[96:99], v[0:15]
	s_setprio 0
	ds_read_b128 v[84:87], v226 offset:49152
	ds_read_b128 v[92:95], v230 offset:49152
	ds_read_b128 v[96:99], v230 offset:53248
	ds_read_b128 v[88:91], v226 offset:53248
	s_setprio 1
	s_add_i32 m0, s19, 0x4100
	s_waitcnt lgkmcnt(6)
	v_mfma_f32_32x32x16_bf16 v[48:63], v[102:105], v[110:113], v[48:63]
	global_load_lds_dwordx4 v124, s[14:15]
	s_add_i32 m0, s19, 0x6100
	s_waitcnt lgkmcnt(5)
	v_mfma_f32_32x32x16_bf16 v[32:47], v[102:105], v[114:117], v[32:47]
	global_load_lds_dwordx4 v125, s[14:15]
	s_waitcnt lgkmcnt(4)
	v_mfma_f32_32x32x16_bf16 v[16:31], v[106:109], v[110:113], v[16:31]
	v_mfma_f32_32x32x16_bf16 v[0:15], v[106:109], v[114:117], v[0:15]
	s_setprio 0
	ds_read_b128 v[102:105], v227 offset:49152
	ds_read_b128 v[110:113], v231 offset:49152
	ds_read_b128 v[114:117], v231 offset:53248
	ds_read_b128 v[106:109], v227 offset:53248
	s_setprio 1
	s_add_i32 m0, s19, 0x8100
	s_waitcnt lgkmcnt(6)
	v_mfma_f32_32x32x16_bf16 v[48:63], v[84:87], v[92:95], v[48:63]
	global_load_lds_dwordx4 v126, s[14:15]
	s_add_i32 m0, s19, 0xa100
	s_waitcnt lgkmcnt(5)
	v_mfma_f32_32x32x16_bf16 v[32:47], v[84:87], v[96:99], v[32:47]
	global_load_lds_dwordx4 v127, s[14:15]
	s_waitcnt lgkmcnt(4)
	v_mfma_f32_32x32x16_bf16 v[16:31], v[88:91], v[92:95], v[16:31]
	v_mfma_f32_32x32x16_bf16 v[0:15], v[88:91], v[96:99], v[0:15]
	s_setprio 0
	s_add_u32 s12, s12, 0x80
	s_addc_u32 s13, s13, 0
	s_add_u32 s14, s14, 0x80
	s_addc_u32 s15, s15, 0
	s_waitcnt lgkmcnt(0)
	s_waitcnt vmcnt(6)
	s_barrier
	ds_read_b128 v[84:87], v232
	ds_read_b128 v[92:95], v236
	ds_read_b128 v[96:99], v236 offset:4096
	ds_read_b128 v[88:91], v232 offset:4096
	s_setprio 1
	v_mfma_f32_32x32x16_bf16 v[48:63], v[102:105], v[110:113], v[48:63]
	v_mfma_f32_32x32x16_bf16 v[32:47], v[102:105], v[114:117], v[32:47]
	v_mfma_f32_32x32x16_bf16 v[16:31], v[106:109], v[110:113], v[16:31]
	v_mfma_f32_32x32x16_bf16 v[0:15], v[106:109], v[114:117], v[0:15]
	s_setprio 0
	ds_read_b128 v[102:105], v233
	ds_read_b128 v[110:113], v237
	ds_read_b128 v[114:117], v237 offset:4096
	ds_read_b128 v[106:109], v233 offset:4096
	s_setprio 1
	s_add_i32 m0, s19, 0xc100
	s_waitcnt lgkmcnt(6)
	v_mfma_f32_32x32x16_bf16 v[48:63], v[84:87], v[92:95], v[48:63]
	global_load_lds_dwordx4 v124, s[12:13]
	s_add_i32 m0, s19, 0xe100
	s_waitcnt lgkmcnt(5)
	v_mfma_f32_32x32x16_bf16 v[32:47], v[84:87], v[96:99], v[32:47]
	global_load_lds_dwordx4 v125, s[12:13]
	s_waitcnt lgkmcnt(4)
	v_mfma_f32_32x32x16_bf16 v[16:31], v[88:91], v[92:95], v[16:31]
	v_mfma_f32_32x32x16_bf16 v[0:15], v[88:91], v[96:99], v[0:15]
	s_setprio 0
	ds_read_b128 v[84:87], v234
	ds_read_b128 v[92:95], v238
	ds_read_b128 v[96:99], v238 offset:4096
	ds_read_b128 v[88:91], v234 offset:4096
	s_setprio 1
	s_add_i32 m0, s19, 0x10100
	s_waitcnt lgkmcnt(6)
	v_mfma_f32_32x32x16_bf16 v[48:63], v[102:105], v[110:113], v[48:63]
	global_load_lds_dwordx4 v124, s[14:15]
	s_add_i32 m0, s19, 0x12100
	s_waitcnt lgkmcnt(5)
	v_mfma_f32_32x32x16_bf16 v[32:47], v[102:105], v[114:117], v[32:47]
	global_load_lds_dwordx4 v125, s[14:15]
	s_waitcnt lgkmcnt(4)
	v_mfma_f32_32x32x16_bf16 v[16:31], v[106:109], v[110:113], v[16:31]
	v_mfma_f32_32x32x16_bf16 v[0:15], v[106:109], v[114:117], v[0:15]
	s_setprio 0
	ds_read_b128 v[102:105], v235
	ds_read_b128 v[110:113], v239
	ds_read_b128 v[114:117], v239 offset:4096
	ds_read_b128 v[106:109], v235 offset:4096
	s_setprio 1
	s_add_i32 m0, s19, 0x14100
	s_waitcnt lgkmcnt(6)
	v_mfma_f32_32x32x16_bf16 v[48:63], v[84:87], v[92:95], v[48:63]
	global_load_lds_dwordx4 v126, s[14:15]
	s_add_i32 m0, s19, 0x16100
	s_waitcnt lgkmcnt(5)
	v_mfma_f32_32x32x16_bf16 v[32:47], v[84:87], v[96:99], v[32:47]
	global_load_lds_dwordx4 v127, s[14:15]
	s_waitcnt lgkmcnt(4)
	v_mfma_f32_32x32x16_bf16 v[16:31], v[88:91], v[92:95], v[16:31]
	v_mfma_f32_32x32x16_bf16 v[0:15], v[88:91], v[96:99], v[0:15]
	s_setprio 0
	s_add_u32 s12, s12, 0x80
	s_addc_u32 s13, s13, 0
	s_add_u32 s14, s14, 0x80
	s_addc_u32 s15, s15, 0
	s_waitcnt lgkmcnt(0)
	s_waitcnt vmcnt(6)
	s_barrier
	ds_read_b128 v[84:87], v224
	ds_read_b128 v[92:95], v228
	ds_read_b128 v[96:99], v228 offset:4096
	ds_read_b128 v[88:91], v224 offset:4096
	s_setprio 1
	v_mfma_f32_32x32x16_bf16 v[48:63], v[102:105], v[110:113], v[48:63]
	v_mfma_f32_32x32x16_bf16 v[32:47], v[102:105], v[114:117], v[32:47]
	v_mfma_f32_32x32x16_bf16 v[16:31], v[106:109], v[110:113], v[16:31]
	v_mfma_f32_32x32x16_bf16 v[0:15], v[106:109], v[114:117], v[0:15]
	s_setprio 0
	ds_read_b128 v[102:105], v225
	ds_read_b128 v[110:113], v229
	ds_read_b128 v[114:117], v229 offset:4096
	ds_read_b128 v[106:109], v225 offset:4096
	s_setprio 1
	s_add_i32 m0, s19, 0x1b900
	s_waitcnt lgkmcnt(6)
	v_mfma_f32_32x32x16_bf16 v[48:63], v[84:87], v[92:95], v[48:63]
	global_load_lds_dwordx4 v124, s[12:13]
	s_add_i32 m0, s19, 0x1d900
	s_waitcnt lgkmcnt(5)
	v_mfma_f32_32x32x16_bf16 v[32:47], v[84:87], v[96:99], v[32:47]
	global_load_lds_dwordx4 v125, s[12:13]
	s_waitcnt lgkmcnt(4)
	v_mfma_f32_32x32x16_bf16 v[16:31], v[88:91], v[92:95], v[16:31]
	v_mfma_f32_32x32x16_bf16 v[0:15], v[88:91], v[96:99], v[0:15]
	s_setprio 0
	ds_read_b128 v[84:87], v226
	ds_read_b128 v[92:95], v230
	ds_read_b128 v[96:99], v230 offset:4096
	ds_read_b128 v[88:91], v226 offset:4096
	s_setprio 1
	s_add_i32 m0, s19, 0x1f900
	s_waitcnt lgkmcnt(6)
	v_mfma_f32_32x32x16_bf16 v[48:63], v[102:105], v[110:113], v[48:63]
	global_load_lds_dwordx4 v124, s[14:15]
	s_add_i32 m0, s19, 0x21900
	s_waitcnt lgkmcnt(5)
	v_mfma_f32_32x32x16_bf16 v[32:47], v[102:105], v[114:117], v[32:47]
	global_load_lds_dwordx4 v125, s[14:15]
	s_waitcnt lgkmcnt(4)
	v_mfma_f32_32x32x16_bf16 v[16:31], v[106:109], v[110:113], v[16:31]
	v_mfma_f32_32x32x16_bf16 v[0:15], v[106:109], v[114:117], v[0:15]
	s_setprio 0
	ds_read_b128 v[102:105], v227
	ds_read_b128 v[110:113], v231
	ds_read_b128 v[114:117], v231 offset:4096
	ds_read_b128 v[106:109], v227 offset:4096
	s_setprio 1
	s_add_i32 m0, s19, 0x23900
	s_waitcnt lgkmcnt(6)
	v_mfma_f32_32x32x16_bf16 v[48:63], v[84:87], v[92:95], v[48:63]
	global_load_lds_dwordx4 v126, s[14:15]
	s_add_i32 m0, s19, 0x25900
	s_waitcnt lgkmcnt(5)
	v_mfma_f32_32x32x16_bf16 v[32:47], v[84:87], v[96:99], v[32:47]
	global_load_lds_dwordx4 v127, s[14:15]
	s_waitcnt lgkmcnt(4)
	v_mfma_f32_32x32x16_bf16 v[16:31], v[88:91], v[92:95], v[16:31]
	v_mfma_f32_32x32x16_bf16 v[0:15], v[88:91], v[96:99], v[0:15]
	s_setprio 0
	s_add_u32 s12, s12, 0x80
	s_addc_u32 s13, s13, 0
	s_add_u32 s14, s14, 0x80
	s_addc_u32 s15, s15, 0
	s_waitcnt lgkmcnt(0)
	s_waitcnt vmcnt(6)
	s_barrier
	ds_read_b128 v[84:87], v224 offset:49152
	ds_read_b128 v[92:95], v228 offset:49152
	ds_read_b128 v[96:99], v228 offset:53248
	ds_read_b128 v[88:91], v224 offset:53248
	s_setprio 1
	v_mfma_f32_32x32x16_bf16 v[48:63], v[102:105], v[110:113], v[48:63]
	v_mfma_f32_32x32x16_bf16 v[32:47], v[102:105], v[114:117], v[32:47]
	v_mfma_f32_32x32x16_bf16 v[16:31], v[106:109], v[110:113], v[16:31]
	v_mfma_f32_32x32x16_bf16 v[0:15], v[106:109], v[114:117], v[0:15]
	s_setprio 0
	ds_read_b128 v[102:105], v225 offset:49152
	ds_read_b128 v[110:113], v229 offset:49152
	ds_read_b128 v[114:117], v229 offset:53248
	ds_read_b128 v[106:109], v225 offset:53248
	s_setprio 1
	s_add_i32 m0, s19, 0x100
	s_waitcnt lgkmcnt(6)
	v_mfma_f32_32x32x16_bf16 v[48:63], v[84:87], v[92:95], v[48:63]
	global_load_lds_dwordx4 v124, s[12:13]
	s_add_i32 m0, s19, 0x2100
	s_waitcnt lgkmcnt(5)
	v_mfma_f32_32x32x16_bf16 v[32:47], v[84:87], v[96:99], v[32:47]
	global_load_lds_dwordx4 v125, s[12:13]
	s_waitcnt lgkmcnt(4)
	v_mfma_f32_32x32x16_bf16 v[16:31], v[88:91], v[92:95], v[16:31]
	v_mfma_f32_32x32x16_bf16 v[0:15], v[88:91], v[96:99], v[0:15]
	s_setprio 0
	ds_read_b128 v[84:87], v226 offset:49152
	ds_read_b128 v[92:95], v230 offset:49152
	ds_read_b128 v[96:99], v230 offset:53248
	ds_read_b128 v[88:91], v226 offset:53248
	s_setprio 1
	s_add_i32 m0, s19, 0x4100
	s_waitcnt lgkmcnt(6)
	v_mfma_f32_32x32x16_bf16 v[48:63], v[102:105], v[110:113], v[48:63]
	global_load_lds_dwordx4 v124, s[14:15]
	s_add_i32 m0, s19, 0x6100
	s_waitcnt lgkmcnt(5)
	v_mfma_f32_32x32x16_bf16 v[32:47], v[102:105], v[114:117], v[32:47]
	global_load_lds_dwordx4 v125, s[14:15]
	s_waitcnt lgkmcnt(4)
	v_mfma_f32_32x32x16_bf16 v[16:31], v[106:109], v[110:113], v[16:31]
	v_mfma_f32_32x32x16_bf16 v[0:15], v[106:109], v[114:117], v[0:15]
	s_setprio 0
	ds_read_b128 v[102:105], v227 offset:49152
	ds_read_b128 v[110:113], v231 offset:49152
	ds_read_b128 v[114:117], v231 offset:53248
	ds_read_b128 v[106:109], v227 offset:53248
	s_setprio 1
	s_add_i32 m0, s19, 0x8100
	s_waitcnt lgkmcnt(6)
	v_mfma_f32_32x32x16_bf16 v[48:63], v[84:87], v[92:95], v[48:63]
	global_load_lds_dwordx4 v126, s[14:15]
	s_add_i32 m0, s19, 0xa100
	s_waitcnt lgkmcnt(5)
	v_mfma_f32_32x32x16_bf16 v[32:47], v[84:87], v[96:99], v[32:47]
	global_load_lds_dwordx4 v127, s[14:15]
	s_waitcnt lgkmcnt(4)
	v_mfma_f32_32x32x16_bf16 v[16:31], v[88:91], v[92:95], v[16:31]
	v_mfma_f32_32x32x16_bf16 v[0:15], v[88:91], v[96:99], v[0:15]
	s_setprio 0
	s_add_u32 s12, s12, 0x80
	s_addc_u32 s13, s13, 0
	s_add_u32 s14, s14, 0x80
	s_addc_u32 s15, s15, 0
	s_waitcnt lgkmcnt(0)
	s_waitcnt vmcnt(6)
	s_barrier
	ds_read_b128 v[84:87], v232
	ds_read_b128 v[92:95], v236
	ds_read_b128 v[96:99], v236 offset:4096
	ds_read_b128 v[88:91], v232 offset:4096
	s_setprio 1
	v_mfma_f32_32x32x16_bf16 v[48:63], v[102:105], v[110:113], v[48:63]
	v_mfma_f32_32x32x16_bf16 v[32:47], v[102:105], v[114:117], v[32:47]
	v_mfma_f32_32x32x16_bf16 v[16:31], v[106:109], v[110:113], v[16:31]
	v_mfma_f32_32x32x16_bf16 v[0:15], v[106:109], v[114:117], v[0:15]
	s_setprio 0
	ds_read_b128 v[102:105], v233
	ds_read_b128 v[110:113], v237
	ds_read_b128 v[114:117], v237 offset:4096
	ds_read_b128 v[106:109], v233 offset:4096
	s_setprio 1
	s_waitcnt lgkmcnt(6)
	v_mfma_f32_32x32x16_bf16 v[48:63], v[84:87], v[92:95], v[48:63]
	s_waitcnt lgkmcnt(5)
	v_mfma_f32_32x32x16_bf16 v[32:47], v[84:87], v[96:99], v[32:47]
	s_waitcnt lgkmcnt(4)
	v_mfma_f32_32x32x16_bf16 v[16:31], v[88:91], v[92:95], v[16:31]
	v_mfma_f32_32x32x16_bf16 v[0:15], v[88:91], v[96:99], v[0:15]
	s_setprio 0
	ds_read_b128 v[84:87], v234
	ds_read_b128 v[92:95], v238
	ds_read_b128 v[96:99], v238 offset:4096
	ds_read_b128 v[88:91], v234 offset:4096
	s_setprio 1
	s_waitcnt lgkmcnt(6)
	v_mfma_f32_32x32x16_bf16 v[48:63], v[102:105], v[110:113], v[48:63]
	s_waitcnt lgkmcnt(5)
	v_mfma_f32_32x32x16_bf16 v[32:47], v[102:105], v[114:117], v[32:47]
	s_waitcnt lgkmcnt(4)
	v_mfma_f32_32x32x16_bf16 v[16:31], v[106:109], v[110:113], v[16:31]
	v_mfma_f32_32x32x16_bf16 v[0:15], v[106:109], v[114:117], v[0:15]
	s_setprio 0
	ds_read_b128 v[102:105], v235
	ds_read_b128 v[110:113], v239
	ds_read_b128 v[114:117], v239 offset:4096
	ds_read_b128 v[106:109], v235 offset:4096
	s_setprio 1
	s_waitcnt lgkmcnt(6)
	v_mfma_f32_32x32x16_bf16 v[48:63], v[84:87], v[92:95], v[48:63]
	s_waitcnt lgkmcnt(5)
	v_mfma_f32_32x32x16_bf16 v[32:47], v[84:87], v[96:99], v[32:47]
	s_waitcnt lgkmcnt(4)
	v_mfma_f32_32x32x16_bf16 v[16:31], v[88:91], v[92:95], v[16:31]
	v_mfma_f32_32x32x16_bf16 v[0:15], v[88:91], v[96:99], v[0:15]
	s_setprio 0
	s_waitcnt lgkmcnt(0)
	s_waitcnt vmcnt(0)
	s_barrier
	ds_read_b128 v[84:87], v224
	ds_read_b128 v[92:95], v228
	ds_read_b128 v[96:99], v228 offset:4096
	ds_read_b128 v[88:91], v224 offset:4096
	s_setprio 1
	v_mfma_f32_32x32x16_bf16 v[48:63], v[102:105], v[110:113], v[48:63]
	v_mfma_f32_32x32x16_bf16 v[32:47], v[102:105], v[114:117], v[32:47]
	v_mfma_f32_32x32x16_bf16 v[16:31], v[106:109], v[110:113], v[16:31]
	v_mfma_f32_32x32x16_bf16 v[0:15], v[106:109], v[114:117], v[0:15]
	s_setprio 0
	ds_read_b128 v[102:105], v225
	ds_read_b128 v[110:113], v229
	ds_read_b128 v[114:117], v229 offset:4096
	ds_read_b128 v[106:109], v225 offset:4096
	s_setprio 1
	s_waitcnt lgkmcnt(6)
	v_mfma_f32_32x32x16_bf16 v[48:63], v[84:87], v[92:95], v[48:63]
	s_waitcnt lgkmcnt(5)
	v_mfma_f32_32x32x16_bf16 v[32:47], v[84:87], v[96:99], v[32:47]
	s_waitcnt lgkmcnt(4)
	v_mfma_f32_32x32x16_bf16 v[16:31], v[88:91], v[92:95], v[16:31]
	v_mfma_f32_32x32x16_bf16 v[0:15], v[88:91], v[96:99], v[0:15]
	s_setprio 0
	ds_read_b128 v[84:87], v226
	ds_read_b128 v[92:95], v230
	ds_read_b128 v[96:99], v230 offset:4096
	ds_read_b128 v[88:91], v226 offset:4096
	s_setprio 1
	s_waitcnt lgkmcnt(6)
	v_mfma_f32_32x32x16_bf16 v[48:63], v[102:105], v[110:113], v[48:63]
	s_waitcnt lgkmcnt(5)
	v_mfma_f32_32x32x16_bf16 v[32:47], v[102:105], v[114:117], v[32:47]
	s_waitcnt lgkmcnt(4)
	v_mfma_f32_32x32x16_bf16 v[16:31], v[106:109], v[110:113], v[16:31]
	v_mfma_f32_32x32x16_bf16 v[0:15], v[106:109], v[114:117], v[0:15]
	s_setprio 0
	ds_read_b128 v[102:105], v227
	ds_read_b128 v[110:113], v231
	ds_read_b128 v[114:117], v231 offset:4096
	ds_read_b128 v[106:109], v227 offset:4096
	s_setprio 1
	s_waitcnt lgkmcnt(6)
	v_mfma_f32_32x32x16_bf16 v[48:63], v[84:87], v[92:95], v[48:63]
	s_waitcnt lgkmcnt(5)
	v_mfma_f32_32x32x16_bf16 v[32:47], v[84:87], v[96:99], v[32:47]
	s_waitcnt lgkmcnt(4)
	v_mfma_f32_32x32x16_bf16 v[16:31], v[88:91], v[92:95], v[16:31]
	v_mfma_f32_32x32x16_bf16 v[0:15], v[88:91], v[96:99], v[0:15]
	s_setprio 0
	s_waitcnt lgkmcnt(0)
	s_waitcnt vmcnt(0)
	s_barrier
